# attention units: gain-row and sink-logit loads hoisted to the top of the full and quarter units (were issued after the staging barrier with exposed latency); quarter-unit vmcnt 6->5
# speedup vs baseline: 1.0014x; 1.0014x over previous
; #define LAS __attribute__((address_space(3)))
; __device__ __forceinline__ void attn_unit(LAS unsigned char* lds, int unit, int mode, const bf16* QKVG, const float* sinks, const float* gain_a, bf16* MIX, float* SSA) {
;     const int tid = threadIdx.x, lane = tid & 63, w = __builtin_amdgcn_readfirstlane(tid >> 6);
;     const int kvh = unit & 1, blk = unit >> 1, nblk = blk & 15, T0 = blk * 128;
;     const int hl = (mode == 0 || mode >= 3) ? w : (4 * (mode - 1) + (w & 3));
;     const int i0 = (mode == 0) ? 0 : (mode <= 2) ? 2 * (w >> 2) : (mode - 3), i1 = (mode == 0) ? 4 : (mode <= 2) ? i0 + 2 : i0 + 1;
;     LAS bf16* Ks = (LAS bf16*)(lds + LDS_KS); LAS bf16* Vt = (LAS bf16*)(lds + LDS_VT); LAS float* SS = (LAS float*)(lds + LDS_SS);
;     const int h = kvh * 8 + hl, q = lane & 31, hh = lane >> 5;
;     SS[tid] = 0.f; SS[tid + 512] = 0.f;
;     const int r8 = lane >> 3, c8 = lane & 7;
;     const bf16* qrow0 = QKVG + (size_t)(T0 + r8) * QP + h * 64 + 8 * c8;
;     const bf16* grow0 = qrow0 + 1280;
;     LAS bf16* WT = (LAS bf16*)(lds + LDS_WT) + w * (32 * KP);
;     LAS bf16* wt_row = WT + r8 * KP + 8 * c8;
;     LAS bf16* wt_frq = WT + q * KP + 8 * hh;
;     LAS bf16* wt_frd = WT + q * KP + 4 * hh;
;     bf16x8 qr[4]; v2u gt[8]; v4u qrow[4], grow[4];
; #pragma unroll
;     for (int k = 0; k < 4; ++k) qrow[k] = __builtin_nontemporal_load((const v4u*)(qrow0 + (size_t)(32 * i0 + 8 * k) * QP));
;     if (mode < 3 || tid < 320) {
;         const int rp = ((mode >= 3) ? 16 * (mode - 3) : 0) + (tid >> 2), qd = tid & 3, row = 2 * rp;
;         const bool valid = (nblk > 0) || (row >= 128);
;         const int tok = valid ? (T0 - 128 + row) : T0;
;         const bf16* src = QKVG + (size_t)tok * QP + 1024 + kvh * 64 + qd * 16;
;         v4u k0[2], k1[2], v0[2], v1[2];
; #pragma unroll
;         for (int c = 0; c < 2; ++c) { k0[c] = *(const v4u*)(src + 8 * c); k1[c] = *(const v4u*)(src + QP + 8 * c); v0[c] = *(const v4u*)(src + 128 + 8 * c); v1[c] = *(const v4u*)(src + QP + 128 + 8 * c);
;             if (!valid) { k0[c] = k1[c] = v0[c] = v1[c] = (v4u){0u, 0u, 0u, 0u}; } }
;     ...
;     const float slope2 = exp2f(-0.5f * (float)(h + 1)) * LOG2E, sink2 = sinks[h] * LOG2E;
;     LAS float* GN = SS + 8 * 128 + w * 64;
;     GN[lane] = gain_a[h * 64 + lane];
.LBB0_290:
	v_writelane_b32 v253, s54, 50
	s_nop 1
	v_writelane_b32 v253, s55, 51
	s_or_b64 exec, exec, s[0:1]
	s_lshl_b32 s0, s33, 11
	s_lshl_b32 s1, s90, 6
	v_readfirstlane_b32 s12, v230
	s_bfe_u32 s91, s98, 0x10003
	s_add_i32 s0, s0, s1
	v_readlane_b32 s2, v253, 50
	s_lshr_b32 s10, s12, 6
	s_and_b32 s92, s0, 0xffffff80
	s_lshl_b32 s0, s91, 3
	v_lshrrev_b32_e32 v127, 3, v231
	v_readlane_b32 s3, v253, 51
	s_add_i32 s13, s10, s0
	v_or_b32_e32 v133, s92, v127
	s_movk_i32 s14, 0x1200
	v_mov_b64_e32 v[8:9], s[2:3]
	v_lshlrev_b32_e32 v2, 3, v230
	s_mov_b32 s1, 0
	v_mov_b32_e32 v131, 0
	v_mad_u64_u32 v[0:1], s[2:3], v133, s14, v[8:9]
	s_lshl_b32 s0, s13, 7
	v_and_b32_e32 v130, 56, v2
	v_lshl_add_u64 v[0:1], v[0:1], 0, s[0:1]
	v_lshlrev_b32_e32 v98, 1, v130
	v_mov_b32_e32 v99, v131
	v_lshl_add_u64 v[100:101], v[0:1], 0, v[98:99]
	s_mov_b32 s0, 0x9000
	v_add_co_u32_e32 v12, vcc, s0, v100
	s_mov_b32 s0, 0x12000
	s_nop 0
	v_addc_co_u32_e32 v13, vcc, 0, v101, vcc
	v_add_co_u32_e32 v0, vcc, s0, v100
	s_mov_b32 s0, 0x1b000
	s_nop 0
	v_addc_co_u32_e32 v1, vcc, 0, v101, vcc
	s_lshl_b32 s11, s13, 6
	v_add_co_u32_e32 v4, vcc, s0, v100
	s_and_b32 s93, s98, 0xf0
	s_nop 0
	v_addc_co_u32_e32 v5, vcc, 0, v101, vcc
	s_cmp_lg_u32 s93, 0
	s_movk_i32 s0, 0xff
	v_lshlrev_b32_e32 v52, 1, v103
	s_cselect_b64 vcc, -1, 0
	v_cmp_lt_u32_e64 s[4:5], s0, v230
	v_add_u32_e32 v10, 0xffffff80, v52
	s_or_b64 s[4:5], vcc, s[4:5]
	v_cndmask_b32_e64 v10, 0, v10, s[4:5]
	v_add_u32_e32 v10, s92, v10
	v_mad_i64_i32 v[8:9], s[2:3], v10, s14, v[8:9]
	s_lshl_b32 s0, s91, 7
	v_lshl_add_u64 v[8:9], v[8:9], 0, s[0:1]
	v_lshlrev_b32_e32 v50, 1, v102
	v_mov_b32_e32 v51, v131
	v_lshl_add_u64 v[32:33], v[8:9], 0, v[50:51]
	s_movk_i32 s0, 0x1000
	v_add_co_u32_e64 v20, s[6:7], s0, v32
	s_nop 1
	v_addc_co_u32_e64 v21, s[6:7], 0, v33, s[6:7]
	v_readlane_b32 s28, v253, 16
	v_readlane_b32 s29, v253, 17
	v_readlane_b32 s24, v253, 12
	v_readlane_b32 s25, v253, 13
	v_or_b32_e32 v232, s11, v231
	v_mov_b32_e32 v233, 0
	v_lshl_add_u64 v[232:233], v[232:233], 2, s[28:29]
	s_lshl_b32 s28, s13, 2
	v_mov_b32_e32 v234, s28
	s_nop 1
	global_load_dword v232, v[232:233], off
	global_load_dword v234, v234, s[24:25]
	s_barrier
	global_load_dwordx4 v[0:3], v[0:1], off nt
	s_nop 0
	global_load_dwordx4 v[4:7], v[4:5], off nt
	s_nop 0
	global_load_dwordx4 v[8:11], v[100:101], off nt
	global_load_dwordx4 v[24:27], v[32:33], off offset:2048
	s_nop 0
	global_load_dwordx4 v[12:15], v[12:13], off nt
	s_nop 0
	global_load_dwordx4 v[16:19], v[32:33], off offset:2304
	global_load_dwordx4 v[28:31], v[20:21], off offset:2560
	s_nop 0
	global_load_dwordx4 v[20:23], v[20:21], off offset:2816
	v_mad_u64_u32 v[48:49], s[2:3], v133, s14, 0
	s_xor_b64 s[2:3], s[4:5], -1
	s_mov_b64 s[4:5], 0x800
	v_add_u32_e32 v137, 0x11400, v81
	v_lshl_add_u64 v[34:35], v[32:33], 0, s[4:5]
	ds_write2st64_b32 v137, v131, v131 offset1:8
	s_and_saveexec_b64 s[4:5], s[2:3]
	s_cbranch_execz .LBB0_292
	s_waitcnt vmcnt(4)
	v_mov_b32_e32 v24, v131
	v_mov_b32_e32 v25, v131
	v_mov_b32_e32 v26, v131
	v_mov_b32_e32 v27, v131
	s_waitcnt vmcnt(1)
	v_mov_b32_e32 v28, v131
	v_mov_b32_e32 v29, v131
	v_mov_b32_e32 v30, v131
	v_mov_b32_e32 v31, v131
	v_mov_b32_e32 v16, v131
	v_mov_b32_e32 v17, v131
	v_mov_b32_e32 v18, v131
	v_mov_b32_e32 v19, v131
	s_waitcnt vmcnt(0)
	v_mov_b32_e32 v20, v131
	v_mov_b32_e32 v21, v131
	v_mov_b32_e32 v22, v131
	v_mov_b32_e32 v23, v131

; #define LAS __attribute__((address_space(3)))
; __device__ __forceinline__ void attn_unit(LAS unsigned char* lds, int unit, int mode, const bf16* QKVG, const float* sinks, const float* gain_a, bf16* MIX, float* SSA) {
;     ...
; #pragma unroll
;         for (int c = 0; c < 2; ++c) { *(LAS v4u*)(Ks + row * KP + qd * 16 + 8 * c) = k0[c]; *(LAS v4u*)(Ks + (row + 1) * KP + qd * 16 + 8 * c) = k1[c]; }
;         const int kq = row & 15, pos = (row & ~15) + (kq & 3) + 4 * ((kq >> 3) & 1) + 8 * ((kq >> 2) & 1);
; #pragma unroll
;         for (int c = 0; c < 2; ++c)
; #pragma unroll
;             for (int e = 0; e < 4; ++e) { const unsigned a = v0[c][e], b = v1[c][e];
;                 *(LAS unsigned*)(Vt + (qd * 16 + 8 * c + 2 * e) * VP + pos) = (a & 0xffffu) | (b << 16);
;                 *(LAS unsigned*)(Vt + (qd * 16 + 8 * c + 2 * e + 1) * VP + pos) = (a >> 16) | (b & 0xffff0000u); }
;     }
;     __syncthreads();
.LBB0_294:
	s_or_b64 exec, exec, s[4:5]
	v_mul_u32_u24_e32 v51, 0x120, v103
	v_add3_u32 v50, 0, v51, v50
	s_waitcnt vmcnt(8)
	ds_write_b128 v50, v[24:27]
	s_waitcnt vmcnt(5)
	ds_write_b128 v50, v[28:31] offset:144
	s_waitcnt vmcnt(3)
	ds_write_b128 v50, v[40:43] offset:16
	s_waitcnt vmcnt(1)
	ds_write_b128 v50, v[44:47] offset:160
	v_and_b32_e32 v24, 0x1f2, v52
	v_and_b32_e32 v25, 4, v103
	v_and_b32_e32 v26, 8, v230
	v_or3_b32 v24, v25, v26, v24
	v_mul_u32_u24_e32 v26, 0x210, v102
	v_lshlrev_b32_e32 v24, 1, v24
	v_and_b32_e32 v25, 0xffff, v16
	v_add3_u32 v24, 0, v26, v24
	v_lshrrev_b32_e32 v16, 16, v16
	s_mov_b32 s2, 0xffff0000
	v_lshl_or_b32 v25, v20, 16, v25
	v_and_or_b32 v16, v20, s2, v16
	v_add_u32_e32 v20, 0x9000, v24
	ds_write2_b32 v20, v25, v16 offset1:132
	v_and_b32_e32 v16, 0xffff, v17
	v_lshrrev_b32_e32 v17, 16, v17
	v_lshl_or_b32 v16, v21, 16, v16
	v_and_or_b32 v17, v21, s2, v17
	v_add_u32_e32 v20, 0x9400, v24
	ds_write2_b32 v20, v16, v17 offset0:8 offset1:140
	v_and_b32_e32 v16, 0xffff, v18
	v_lshrrev_b32_e32 v17, 16, v18
	v_lshl_or_b32 v16, v22, 16, v16
	v_and_or_b32 v17, v22, s2, v17
	v_add_u32_e32 v18, 0x9800, v24
	ds_write2_b32 v18, v16, v17 offset0:16 offset1:148
	v_and_b32_e32 v16, 0xffff, v19
	v_lshrrev_b32_e32 v17, 16, v19
	v_lshl_or_b32 v16, v23, 16, v16
	v_and_or_b32 v17, v23, s2, v17
	v_add_u32_e32 v18, 0x9c00, v24
	ds_write2_b32 v18, v16, v17 offset0:24 offset1:156
	v_and_b32_e32 v16, 0xffff, v32
	v_lshrrev_b32_e32 v17, 16, v32
	s_waitcnt vmcnt(0)
	v_lshl_or_b32 v16, v36, 16, v16
	v_and_or_b32 v17, v36, s2, v17
	v_add_u32_e32 v18, 0xa000, v24
	ds_write2_b32 v18, v16, v17 offset0:32 offset1:164
	v_and_b32_e32 v16, 0xffff, v33
	v_lshrrev_b32_e32 v17, 16, v33
	v_lshl_or_b32 v16, v37, 16, v16
	v_and_or_b32 v17, v37, s2, v17
	v_add_u32_e32 v18, 0xa400, v24
	ds_write2_b32 v18, v16, v17 offset0:40 offset1:172
	v_and_b32_e32 v16, 0xffff, v34
	v_lshrrev_b32_e32 v17, 16, v34
	v_lshl_or_b32 v16, v38, 16, v16
	v_and_or_b32 v17, v38, s2, v17
	v_add_u32_e32 v18, 0xa800, v24
	ds_write2_b32 v18, v16, v17 offset0:48 offset1:180
	v_and_b32_e32 v16, 0xffff, v35
	v_lshrrev_b32_e32 v17, 16, v35
	v_lshl_or_b32 v16, v39, 16, v16
	v_and_or_b32 v17, v39, s2, v17
	v_add_u32_e32 v18, 0xac00, v24
	v_readlane_b32 s16, v253, 4
	ds_write2_b32 v18, v16, v17 offset0:56 offset1:188
	v_or_b32_e32 v16, s11, v231
	v_mov_b32_e32 v17, 0
	v_readlane_b32 s28, v253, 16
	v_readlane_b32 s29, v253, 17
	s_add_i32 s2, s13, 1
	v_cvt_f32_u32_e32 v20, s2
	v_lshl_add_u64 v[18:19], v[16:17], 2, s[28:29]
	s_waitcnt lgkmcnt(0)
	s_barrier
; #define LAS __attribute__((address_space(3)))
; __device__ __forceinline__ void attn_unit(LAS unsigned char* lds, int unit, int mode, const bf16* QKVG, const float* sinks, const float* gain_a, bf16* MIX, float* SSA) {
;     ...
;     constexpr float LOG2E = 1.4426950408889634f;
;     const float slope2 = exp2f(-0.5f * (float)(h + 1)) * LOG2E, sink2 = sinks[h] * LOG2E;
;     LAS float* GN = SS + 8 * 128 + w * 64;
;     GN[lane] = gain_a[h * 64 + lane];
; #pragma unroll
;     for (int k = 0; k < 4; ++k) *(LAS v4u*)(wt_row + 8 * k * KP) = qrow[k];
; #pragma unroll
;     for (int s = 0; s < 4; ++s) qr[s] = *(const LAS bf16x8*)(wt_frq + 16 * s);
;     for (int i = i0; i < i1; ++i) {
;         const int inx = (i < 3) ? (i + 1) : 3;
; #pragma unroll
;         for (int k = 0; k < 4; ++k) qrow[k] = __builtin_nontemporal_load((const v4u*)(qrow0 + (size_t)(32 * inx + 8 * k) * QP));
; #pragma unroll
;         for (int k = 0; k < 4; ++k) grow[k] = __builtin_nontemporal_load((const v4u*)(grow0 + (size_t)(32 * i + 8 * k) * QP));
;         int qq = q - 4 * hh; asm volatile("" : "+v"(qq));
;         float base = slope2 * (float)(4 * hh); asm volatile("" : "+v"(base));
;         f32x16 st[5];
; #pragma unroll
;         for (int j = 0; j < 5; ++j) {
;             const bool tile_ok = !(nblk == 0 && (i + j) < 4);
;             const float sl = tile_ok ? slope2 : 0.f, bs = tile_ok ? base : -INFINITY;
; #pragma unroll
;             for (int r = 0; r < 16; ++r) st[j][r] = fmaf(sl, (float)((r & 3) + 8 * (r >> 2) + 32 * j), bs);
	s_mul_i32 s0, s10, 0x1200
	s_add_i32 s0, s0, 0
	v_mul_f32_e32 v21, -0.5, v20
	s_mov_b32 s2, 0xc2fc0000
	s_add_i32 s0, s0, 0x12c00
	v_cmp_gt_f32_e64 s[4:5], s2, v21
	v_mov_b32_e32 v22, 0x42800000
	s_and_b64 s[2:3], s[4:5], exec
	v_cndmask_b32_e64 v18, 0, v22, s[4:5]
	s_cselect_b32 s4, 0xffffffc0, 0
	s_lshl_b32 s2, s13, 2
	v_readlane_b32 s24, v253, 12
	v_readlane_b32 s25, v253, 13
	v_mov_b32_e32 v19, s2
	v_lshrrev_b32_e32 v136, 5, v231
	v_and_b32_e32 v134, 31, v230
	s_movk_i32 s2, 0x90
	v_lshlrev_b32_e32 v21, 4, v136
	v_mul_u32_u24_e32 v123, 0x90, v127
	v_mad_u32_u24 v22, v134, s2, v21
	v_fmac_f32_e32 v18, -0.5, v20
	v_add3_u32 v138, s0, v123, v98
	v_exp_f32_e32 v18, v18
	v_add_u32_e32 v139, s0, v22
	s_and_b32 s0, s12, 0x3fffffc0
	s_lshl_b32 s0, s0, 2
	s_add_i32 s0, s0, 0
	s_add_i32 s0, s0, 0x12400
	v_lshlrev_b32_e32 v135, 2, v136
	v_ldexp_f32 v18, v18, s4
	v_lshl_add_u32 v23, v231, 2, s0
	s_waitcnt vmcnt(1)
	ds_write_b32 v23, v232
	ds_write_b128 v138, v[8:11]
	ds_write_b128 v138, v[12:15] offset:1152
	ds_write_b128 v138, v[0:3] offset:2304
	ds_write_b128 v138, v[4:7] offset:3456
	v_mul_f32_e32 v104, 0x3fb8aa3b, v18
	v_cvt_f32_ubyte0_e32 v0, v135
	v_mul_f32_e32 v142, v104, v0
	v_or_b32_e32 v0, 0x80, v135
	v_add_u32_e32 v144, s0, v21
	s_lshl_b32 s0, s10, 9
	s_lshl_b32 s6, s11, 1
	v_cvt_f32_ubyte0_e32 v143, v0
	v_mul_u32_u24_e32 v0, 0x210, v134
	s_add_u32 s4, s94, s6
	v_readlane_b32 s17, v253, 5
	v_readlane_b32 s18, v253, 6
	v_readlane_b32 s19, v253, 7
	v_readlane_b32 s20, v253, 8
	v_readlane_b32 s21, v253, 9
	v_readlane_b32 s22, v253, 10
	v_readlane_b32 s23, v253, 11
	v_readlane_b32 s26, v253, 14
	v_readlane_b32 s27, v253, 15
	v_readlane_b32 s30, v253, 18
	v_readlane_b32 s31, v253, 19
	v_writelane_b32 v253, s94, 52
	s_addc_u32 s5, s95, 0
	v_mov_b32_e32 v99, v17
	v_add3_u32 v0, v0, v21, 0
	v_lshl_add_u64 v[110:111], s[4:5], 0, v[98:99]
	v_add_u32_e32 v99, 0x9000, v0
	v_and_b32_e32 v0, 7, v230
	v_lshlrev_b32_e32 v16, 4, v0
	s_add_u32 s4, s96, s6
	v_lshl_add_u64 v[0:1], v[48:49], 0, v[16:17]
	s_addc_u32 s5, s97, 0
	s_add_i32 s0, s0, 0
	v_lshlrev_b32_e32 v129, 3, v136
	v_lshl_add_u64 v[112:113], s[4:5], 0, v[0:1]
	v_lshl_add_u32 v0, v134, 2, s0
	v_sub_u32_e32 v20, 0, v129
	s_mov_b32 s2, 0x42800000
	v_cndmask_b32_e32 v106, 0, v104, vcc
	v_add_u32_e32 v146, 0x11400, v0
	s_mov_b32 s10, 2.0
	s_mov_b32 s12, 0x41000000
	s_mov_b32 s14, 0x41200000
	s_mov_b32 s16, 0x41800000
	s_mov_b32 s18, 0x41900000
	s_mov_b32 s20, 0x41c00000
	s_mov_b32 s22, 0x41d00000
	s_mov_b32 s24, 0x42680000
	s_mov_b32 s26, 0x42600000
	s_mov_b32 s28, 0x42480000
	s_mov_b32 s30, 0x42400000
	s_mov_b32 s34, 0x42280000
	s_mov_b32 s36, 0x42200000
	s_mov_b32 s38, 0x42080000
	s_mov_b32 s40, 0x42000000
	s_mov_b32 s42, 0x42b40000
	s_mov_b32 s44, 0x42b00000
	s_mov_b32 s46, 0x42a40000
	s_mov_b32 s48, 0x42a00000
	s_mov_b32 s50, 0x42940000
	s_mov_b32 s52, 0x42900000
	s_mov_b32 s54, 0x42840000
	s_mov_b32 s56, 0x42f40000
	s_mov_b32 s58, 0x42f00000
	s_mov_b32 s60, 0x42e40000
	s_mov_b32 s62, 0x42e00000
	s_mov_b32 s64, 0x42d40000
	s_mov_b32 s66, 0x42d00000
	s_mov_b32 s68, 0x42c40000
	s_mov_b32 s70, 0x42c00000
	s_mov_b32 s72, 0x431a0000
	s_mov_b32 s74, 0x43180000
	s_mov_b32 s76, 0x43120000
	s_mov_b32 s78, 0x43100000
	s_mov_b32 s80, 0x430a0000
	s_mov_b32 s82, 0x43080000
	s_mov_b32 s84, 0x43020000
	s_mov_b32 s86, 0x43000000
	v_mbcnt_lo_u32_b32 v0, -1, 0
	v_mul_u32_u24_e32 v125, 0x90, v134
	s_mov_b32 s3, 0x42820000
	s_waitcnt vmcnt(0)
	v_mul_f32_e32 v140, 0x3fb8aa3b, v234
	v_sub_u32_e32 v141, v134, v135
	v_mov_b32_e32 v107, v106
	v_mov_b32_e32 v108, v104
	v_mov_b32_e32 v109, v104
	v_add_u32_e32 v145, 0, v22
	s_mov_b32 s11, 0x40400000
	s_mov_b32 s13, 0x41100000
	s_mov_b32 s15, 0x41300000
	s_mov_b32 s17, 0x41880000
	s_mov_b32 s19, 0x41980000
	s_mov_b32 s21, 0x41c80000
	s_mov_b32 s23, 0x41d80000
	s_mov_b32 s25, 0x426c0000
	s_mov_b32 s27, 0x42640000
	s_mov_b32 s29, 0x424c0000
	s_mov_b32 s31, 0x42440000
	s_mov_b32 s35, 0x422c0000
	s_mov_b32 s37, 0x42240000
	s_mov_b32 s39, 0x420c0000
	s_mov_b32 s41, 0x42040000
	s_mov_b32 s43, 0x42b60000
	s_mov_b32 s45, 0x42b20000
	s_mov_b32 s47, 0x42a60000
	s_mov_b32 s49, 0x42a20000
	s_mov_b32 s51, 0x42960000
	s_mov_b32 s53, 0x42920000
	s_mov_b32 s55, 0x42860000
	s_mov_b32 s57, 0x42f60000
	s_mov_b32 s59, 0x42f20000
	s_mov_b32 s61, 0x42e60000
	s_mov_b32 s63, 0x42e20000
	s_mov_b32 s65, 0x42d60000
	s_mov_b32 s67, 0x42d20000
	s_mov_b32 s69, 0x42c60000
	s_mov_b32 s71, 0x42c20000
	s_mov_b32 s73, 0x431b0000
	s_mov_b32 s75, 0x43190000
	s_mov_b32 s77, 0x43130000
	s_mov_b32 s79, 0x43110000
	s_mov_b32 s81, 0x430b0000
	s_mov_b32 s83, 0x43090000
	s_mov_b32 s85, 0x43030000
	s_mov_b32 s87, 0x43010000
	v_mbcnt_hi_u32_b32 v147, -1, v0
	v_add_u32_e32 v148, v139, v20
	v_mov_b32_e32 v150, 0x1200
	v_mov_b32_e32 v151, 0xff800000
	s_mov_b32 s0, 32
	v_cmp_gt_u32_e64 s[4:5], 32, v231
	s_mov_b64 s[88:89], 0
	v_writelane_b32 v253, s95, 53
	s_branch .LBB0_296

; #define LAS __attribute__((address_space(3)))
; __device__ __forceinline__ void attn_unit(LAS unsigned char* lds, int unit, int mode, const bf16* QKVG, const float* sinks, const float* gain_a, bf16* MIX, float* SSA) {
;     const int tid = threadIdx.x, lane = tid & 63, w = __builtin_amdgcn_readfirstlane(tid >> 6);
;     const int kvh = unit & 1, blk = unit >> 1, nblk = blk & 15, T0 = blk * 128;
;     const int hl = (mode == 0 || mode >= 3) ? w : (4 * (mode - 1) + (w & 3));
;     const int i0 = (mode == 0) ? 0 : (mode <= 2) ? 2 * (w >> 2) : (mode - 3), i1 = (mode == 0) ? 4 : (mode <= 2) ? i0 + 2 : i0 + 1;
;     LAS bf16* Ks = (LAS bf16*)(lds + LDS_KS); LAS bf16* Vt = (LAS bf16*)(lds + LDS_VT); LAS float* SS = (LAS float*)(lds + LDS_SS);
;     const int h = kvh * 8 + hl, q = lane & 31, hh = lane >> 5;
;     SS[tid] = 0.f; SS[tid + 512] = 0.f;
;     const int r8 = lane >> 3, c8 = lane & 7;
;     const bf16* qrow0 = QKVG + (size_t)(T0 + r8) * QP + h * 64 + 8 * c8;
;     const bf16* grow0 = qrow0 + 1280;
;     LAS bf16* WT = (LAS bf16*)(lds + LDS_WT) + w * (32 * KP);
;     LAS bf16* wt_row = WT + r8 * KP + 8 * c8;
;     LAS bf16* wt_frq = WT + q * KP + 8 * hh;
;     LAS bf16* wt_frd = WT + q * KP + 4 * hh;
;     bf16x8 qr[4]; v2u gt[8]; v4u qrow[4], grow[4];
; #pragma unroll
;     for (int k = 0; k < 4; ++k) qrow[k] = __builtin_nontemporal_load((const v4u*)(qrow0 + (size_t)(32 * i0 + 8 * k) * QP));
;     if (mode < 3 || tid < 320) {
;         const int rp = ((mode >= 3) ? 16 * (mode - 3) : 0) + (tid >> 2), qd = tid & 3, row = 2 * rp;
;         const bool valid = (nblk > 0) || (row >= 128);
;         const int tok = valid ? (T0 - 128 + row) : T0;
;         const bf16* src = QKVG + (size_t)tok * QP + 1024 + kvh * 64 + qd * 16;
;         v4u k0[2], k1[2], v0[2], v1[2];
; #pragma unroll
;         for (int c = 0; c < 2; ++c) { k0[c] = *(const v4u*)(src + 8 * c); k1[c] = *(const v4u*)(src + QP + 8 * c); v0[c] = *(const v4u*)(src + 128 + 8 * c); v1[c] = *(const v4u*)(src + QP + 128 + 8 * c);
;             if (!valid) { k0[c] = k1[c] = v0[c] = v1[c] = (v4u){0u, 0u, 0u, 0u}; } }
;     ...
;     const float slope2 = exp2f(-0.5f * (float)(h + 1)) * LOG2E, sink2 = sinks[h] * LOG2E;
;     LAS float* GN = SS + 8 * 128 + w * 64;
;     GN[lane] = gain_a[h * 64 + lane];
.LBB0_303:
	s_lshl_b32 s0, s33, 5
	s_lshr_b32 s1, s98, 5
	s_add_i32 s5, s0, s1
	v_readfirstlane_b32 s6, v230
	s_bfe_u32 s10, s98, 0x10005
	s_lshr_b32 s0, s5, 1
	s_lshr_b32 s13, s6, 6
	s_lshl_b32 s11, s0, 7
	s_lshl_b32 s0, s10, 3
	s_add_i32 s7, s13, s0
	v_readlane_b32 s28, v253, 16
	v_readlane_b32 s29, v253, 17
	v_readlane_b32 s24, v253, 12
	v_readlane_b32 s25, v253, 13
	s_lshl_b32 s0, s7, 6
	v_or_b32_e32 v232, s0, v231
	v_mov_b32_e32 v233, 0
	v_lshl_add_u64 v[232:233], v[232:233], 2, s[28:29]
	s_lshl_b32 s28, s7, 2
	v_mov_b32_e32 v141, s28
	s_nop 1
	global_load_dword v232, v[232:233], off
	global_load_dword v141, v141, s[24:25]
	v_or_b32_e32 v136, s11, v127
	s_movk_i32 s4, 0x1200
	v_mov_b64_e32 v[0:1], s[54:55]
	s_mov_b32 s3, 0
	v_mad_u64_u32 v[0:1], s[0:1], v136, s4, v[0:1]
	s_lshl_b32 s2, s7, 7
	s_bfe_u32 s12, s98, 0x20003
	v_lshl_add_u64 v[0:1], v[0:1], 0, s[2:3]
	v_lshl_add_u64 v[50:51], v[130:131], 1, v[0:1]
	s_mul_i32 s2, s12, 0x24000
	v_lshl_add_u64 v[48:49], v[50:51], 0, s[2:3]
	s_mov_b32 s0, 0x9000
	v_add_co_u32_e32 v4, vcc, s0, v48
	s_movk_i32 s0, 0x140
	s_nop 0
	v_addc_co_u32_e32 v5, vcc, 0, v49, vcc
	v_add_co_u32_e32 v8, vcc, 0x12000, v48
	global_load_dwordx4 v[0:3], v[48:49], off nt
	s_nop 0
	global_load_dwordx4 v[4:7], v[4:5], off nt
	v_addc_co_u32_e32 v9, vcc, 0, v49, vcc
	v_add_co_u32_e32 v12, vcc, 0x1b000, v48
	v_add_u32_e32 v81, 0x11400, v81
	s_nop 0
	v_addc_co_u32_e32 v13, vcc, 0, v49, vcc
	global_load_dwordx4 v[8:11], v[8:9], off nt
	s_nop 0
	global_load_dwordx4 v[12:15], v[12:13], off nt
	v_mov_b32_e32 v53, 0
	s_lshl_b32 s14, s7, 6
	s_bfe_u32 s18, s5, 0x40001
	v_cmp_gt_u32_e32 vcc, s0, v230
	ds_write2st64_b32 v81, v53, v53 offset1:8
	s_and_saveexec_b64 s[0:1], vcc
	s_cbranch_execz .LBB0_309
	v_lshl_add_u32 v54, s12, 4, v103
	s_cmp_lg_u32 s18, 0
	v_lshlrev_b32_e32 v55, 1, v54
	s_cselect_b64 s[16:17], -1, 0
	v_cmp_lt_u32_e32 vcc, 63, v54
	s_add_i32 s2, s11, 0xffffff80
	v_add_u32_e32 v16, s2, v55
	v_mov_b32_e32 v17, s11
	s_or_b64 vcc, s[16:17], vcc
	v_cndmask_b32_e32 v18, v17, v16, vcc
	v_mov_b64_e32 v[16:17], s[54:55]
	v_mad_i64_i32 v[16:17], s[4:5], v18, s4, v[16:17]
	s_lshl_b32 s2, s10, 7
	v_lshl_add_u64 v[16:17], v[16:17], 0, s[2:3]
	v_lshlrev_b32_e32 v52, 1, v102
	v_lshl_add_u64 v[32:33], v[16:17], 0, v[52:53]
	s_movk_i32 s15, 0x1000
	v_add_co_u32_e64 v20, s[4:5], s15, v32
	s_xor_b64 s[2:3], vcc, -1
	s_nop 0
	v_addc_co_u32_e64 v21, s[4:5], 0, v33, s[4:5]
	global_load_dwordx4 v[24:27], v[32:33], off offset:2048
	global_load_dwordx4 v[16:19], v[32:33], off offset:2304
	global_load_dwordx4 v[28:31], v[20:21], off offset:2560
	s_nop 0
	global_load_dwordx4 v[20:23], v[20:21], off offset:2816
	s_mov_b64 s[4:5], 0x800
	v_lshl_add_u64 v[34:35], v[32:33], 0, s[4:5]
	s_and_saveexec_b64 s[4:5], s[2:3]
	s_cbranch_execz .LBB0_306
	s_waitcnt vmcnt(3)
	v_mov_b32_e32 v24, 0
	v_mov_b32_e32 v25, v24
	v_mov_b32_e32 v26, v24
	v_mov_b32_e32 v27, v24
	s_waitcnt vmcnt(1)
	v_mov_b32_e32 v28, v24
	v_mov_b32_e32 v29, v24
	v_mov_b32_e32 v30, v24
	v_mov_b32_e32 v31, v24
	v_mov_b32_e32 v16, v24
	v_mov_b32_e32 v17, v24
	v_mov_b32_e32 v18, v24
	v_mov_b32_e32 v19, v24
	s_waitcnt vmcnt(0)
	v_mov_b32_e32 v20, v24
	v_mov_b32_e32 v21, v24
	v_mov_b32_e32 v22, v24
	v_mov_b32_e32 v23, v24

; #define LAS __attribute__((address_space(3)))
; __device__ __forceinline__ void attn_unit(LAS unsigned char* lds, int unit, int mode, const bf16* QKVG, const float* sinks, const float* gain_a, bf16* MIX, float* SSA) {
;     ...
;     __syncthreads();
;     constexpr float LOG2E = 1.4426950408889634f;
;     const float slope2 = exp2f(-0.5f * (float)(h + 1)) * LOG2E, sink2 = sinks[h] * LOG2E;
;     LAS float* GN = SS + 8 * 128 + w * 64;
;     GN[lane] = gain_a[h * 64 + lane];
; #pragma unroll
;     for (int k = 0; k < 4; ++k) *(LAS v4u*)(wt_row + 8 * k * KP) = qrow[k];
; #pragma unroll
;     for (int s = 0; s < 4; ++s) qr[s] = *(const LAS bf16x8*)(wt_frq + 16 * s);
;     for (int i = i0; i < i1; ++i) {
;         const int inx = (i < 3) ? (i + 1) : 3;
; #pragma unroll
;         for (int k = 0; k < 4; ++k) qrow[k] = __builtin_nontemporal_load((const v4u*)(qrow0 + (size_t)(32 * inx + 8 * k) * QP));
; #pragma unroll
;         for (int k = 0; k < 4; ++k) grow[k] = __builtin_nontemporal_load((const v4u*)(grow0 + (size_t)(32 * i + 8 * k) * QP));
;         int qq = q - 4 * hh; asm volatile("" : "+v"(qq));
;         float base = slope2 * (float)(4 * hh); asm volatile("" : "+v"(base));
;         f32x16 st[5];
; #pragma unroll
;         for (int j = 0; j < 5; ++j) {
;             const bool tile_ok = !(nblk == 0 && (i + j) < 4);
;             const float sl = tile_ok ? slope2 : 0.f, bs = tile_ok ? base : -INFINITY;
; #pragma unroll
;             for (int r = 0; r < 16; ++r) st[j][r] = fmaf(sl, (float)((r & 3) + 8 * (r >> 2) + 32 * j), bs);
.LBB0_309:
	s_or_b64 exec, exec, s[0:1]
	v_readlane_b32 s36, v253, 4
	v_readlane_b32 s44, v253, 12
	v_readlane_b32 s45, v253, 13
	v_readlane_b32 s46, v253, 14
	v_readlane_b32 s47, v253, 15
	v_readlane_b32 s48, v253, 16
	v_readlane_b32 s49, v253, 17
	s_mov_b64 s[24:25], s[44:45]
	v_or_b32_e32 v132, s14, v231
	v_mov_b32_e32 v133, 0
	s_mov_b64 s[28:29], s[48:49]
	v_lshl_add_u64 v[16:17], v[132:133], 2, s[28:29]
	s_waitcnt lgkmcnt(0)
	s_barrier
	s_add_i32 s4, s7, 1
	v_cvt_f32_u32_e32 v20, s4
	s_mul_i32 s0, s13, 0x1200
	s_add_i32 s0, s0, 0
	v_lshlrev_b32_e32 v16, 1, v130
	s_add_i32 s0, s0, 0x12c00
	s_mov_b32 s5, 0xc2fc0000
	v_add3_u32 v137, s0, v123, v16
	v_mul_f32_e32 v16, -0.5, v20
	v_cmp_gt_f32_e32 vcc, s5, v16
	v_mov_b32_e32 v18, 0x42800000
	s_and_b64 s[4:5], vcc, exec
	v_lshlrev_b32_e32 v17, 1, v129
	v_add_u32_e32 v139, s0, v125
	v_cndmask_b32_e32 v16, 0, v18, vcc
	s_cselect_b32 s0, 0xffffffc0, 0
	s_lshl_b32 s4, s7, 2
	s_and_b32 s5, s6, 0x3fffffc0
	v_add_u32_e32 v138, 0, v17
	v_add_u32_e32 v25, v139, v17
	v_fmac_f32_e32 v16, -0.5, v20
	v_mov_b32_e32 v17, s4
	s_lshl_b32 s4, s5, 2
	v_exp_f32_e32 v16, v16
	s_add_i32 s16, s4, 0
	s_add_i32 s16, s16, 0x12400
	s_cmp_lg_u32 s18, 0
	s_cselect_b64 vcc, -1, 0
	s_add_i32 s17, s12, 1
	v_ldexp_f32 v16, v16, s0
	s_lshl_b32 s0, s17, 5
	s_cmp_eq_u32 s12, 3
	s_cselect_b64 s[6:7], -1, 0
	s_and_b64 s[4:5], s[6:7], exec
	v_cvt_f32_u32_e32 v19, v135
	s_cselect_b32 s0, 0x60, s0
	s_mov_b32 s1, 0
	s_mulk_i32 s0, 0x1200
	s_mov_b32 s19, 0x9000
	v_mul_f32_e32 v132, 0x3fb8aa3b, v16
	v_lshl_add_u64 v[16:17], v[50:51], 0, s[0:1]
	v_add_co_u32_e64 v18, s[4:5], s19, v16
	s_mov_b32 s20, 0x12000
	v_mul_f32_e32 v64, v132, v19
	v_addc_co_u32_e64 v19, s[4:5], 0, v17, s[4:5]
	v_add_co_u32_e64 v20, s[4:5], s20, v16
	s_mov_b32 s21, 0x1b000
	s_nop 0
	v_addc_co_u32_e64 v21, s[4:5], 0, v17, s[4:5]
	v_add_co_u32_e64 v22, s[4:5], s21, v16
	v_lshl_add_u32 v26, v231, 2, s16
	s_nop 0
	v_addc_co_u32_e64 v23, s[4:5], 0, v17, s[4:5]
	global_load_dwordx4 v[98:101], v[48:49], off offset:2560 nt
	global_load_dwordx4 v[82:85], v[16:17], off nt
	global_load_dwordx4 v[86:89], v[18:19], off nt
	global_load_dwordx4 v[90:93], v[20:21], off nt
	global_load_dwordx4 v[94:97], v[22:23], off nt
	v_sub_u32_e32 v140, v134, v135
	v_mov_b32_e32 v146, 0xff800000
	s_lshl_b32 s15, s12, 5
	s_mov_b32 s2, 0x42800000
	s_mov_b32 s3, 0x42820000
	v_readlane_b32 s37, v253, 5
	v_readlane_b32 s38, v253, 6
	v_readlane_b32 s39, v253, 7
	v_readlane_b32 s40, v253, 8
	s_waitcnt vmcnt(5)
	ds_write_b32 v26, v232
	ds_write_b128 v137, v[0:3]
	ds_write_b128 v137, v[4:7] offset:1152
	ds_write_b128 v137, v[8:11] offset:2304
	ds_write_b128 v137, v[12:15] offset:3456
	v_add_co_u32_e64 v0, s[4:5], s19, v48
	ds_read_b128 v[114:117], v25 offset:96
	ds_read_b128 v[118:121], v25 offset:64
	ds_read_b128 v[126:129], v25
	ds_read_b128 v[122:125], v25 offset:32
	v_addc_co_u32_e64 v1, s[4:5], 0, v49, s[4:5]
	v_add_co_u32_e64 v2, s[4:5], s20, v48
	v_readlane_b32 s41, v253, 9
	s_nop 0
	v_addc_co_u32_e64 v3, s[4:5], 0, v49, s[4:5]
	global_load_dwordx4 v[102:105], v[0:1], off offset:2560 nt
	global_load_dwordx4 v[106:109], v[2:3], off offset:2560 nt
	v_add_co_u32_e64 v0, s[4:5], s21, v48
	v_readlane_b32 s42, v253, 10
	s_nop 0
	v_addc_co_u32_e64 v1, s[4:5], 0, v49, s[4:5]
	s_mov_b32 s4, 2.0
	global_load_dwordx4 v[110:113], v[0:1], off offset:2560 nt
	v_cndmask_b32_e32 v0, 0, v132, vcc
	v_cndmask_b32_e32 v2, v146, v64, vcc
	s_mov_b32 s5, 0x40400000
	v_pk_fma_f32 v[50:51], v[0:1], s[4:5], v[2:3] op_sel_hi:[0,1,0]
	s_mov_b32 s4, 0x41000000
	s_mov_b32 s5, 0x41100000
	v_pk_fma_f32 v[52:53], v[0:1], s[4:5], v[2:3] op_sel_hi:[0,1,0]
	s_mov_b32 s4, 0x41200000
	s_mov_b32 s5, 0x41300000
	v_pk_fma_f32 v[54:55], v[0:1], s[4:5], v[2:3] op_sel_hi:[0,1,0]
	s_mov_b32 s4, 0x41800000
	s_mov_b32 s5, 0x41880000
	v_pk_fma_f32 v[56:57], v[0:1], s[4:5], v[2:3] op_sel_hi:[0,1,0]
	s_mov_b32 s4, 0x41900000
	s_mov_b32 s5, 0x41980000
	v_pk_fma_f32 v[58:59], v[0:1], s[4:5], v[2:3] op_sel_hi:[0,1,0]
	s_mov_b32 s4, 0x41c00000
	s_mov_b32 s5, 0x41c80000
	v_pk_fma_f32 v[60:61], v[0:1], s[4:5], v[2:3] op_sel_hi:[0,1,0]
	s_mov_b32 s4, 0x41d00000
	s_mov_b32 s5, 0x41d80000
	v_pk_fma_f32 v[62:63], v[0:1], s[4:5], v[2:3] op_sel_hi:[0,1,0]
	s_or_b64 s[4:5], vcc, s[6:7]
	v_fma_f32 v48, 0, v0, v2
	v_add_f32_e32 v49, v0, v2
	v_cndmask_b32_e64 v0, 0, v132, s[4:5]
	v_cndmask_b32_e64 v2, v146, v64, s[4:5]
	s_mov_b32 s4, 0x42680000
	s_mov_b32 s5, 0x426c0000
	v_pk_fma_f32 v[46:47], v[0:1], s[4:5], v[2:3] op_sel_hi:[0,1,0]
	s_mov_b32 s4, 0x42600000
	s_mov_b32 s5, 0x42640000
	v_pk_fma_f32 v[44:45], v[0:1], s[4:5], v[2:3] op_sel_hi:[0,1,0]
	s_mov_b32 s4, 0x42480000
	s_mov_b32 s5, 0x424c0000
	v_pk_fma_f32 v[42:43], v[0:1], s[4:5], v[2:3] op_sel_hi:[0,1,0]
	s_mov_b32 s4, 0x42400000
	s_mov_b32 s5, 0x42440000
	v_pk_fma_f32 v[40:41], v[0:1], s[4:5], v[2:3] op_sel_hi:[0,1,0]
	s_mov_b32 s4, 0x42280000
	s_mov_b32 s5, 0x422c0000
	v_pk_fma_f32 v[38:39], v[0:1], s[4:5], v[2:3] op_sel_hi:[0,1,0]
	s_mov_b32 s4, 0x42200000
	s_mov_b32 s5, 0x42240000
	v_pk_fma_f32 v[36:37], v[0:1], s[4:5], v[2:3] op_sel_hi:[0,1,0]
	s_mov_b32 s4, 0x42080000
	s_mov_b32 s5, 0x420c0000
	v_pk_fma_f32 v[34:35], v[0:1], s[4:5], v[2:3] op_sel_hi:[0,1,0]
	s_mov_b32 s4, 0x42000000
	s_mov_b32 s5, 0x42040000
	s_cmp_gt_u32 s12, 1
	v_pk_fma_f32 v[32:33], v[0:1], s[4:5], v[2:3] op_sel_hi:[0,1,0]
	s_cselect_b64 s[4:5], -1, 0
	s_or_b64 vcc, vcc, s[4:5]
	s_mov_b32 s4, 0x42b40000
	v_cndmask_b32_e32 v0, 0, v132, vcc
	v_cndmask_b32_e32 v2, v146, v64, vcc
	s_mov_b32 s5, 0x42b60000
	v_pk_fma_f32 v[30:31], v[0:1], s[4:5], v[2:3] op_sel_hi:[0,1,0]
	s_mov_b32 s4, 0x42b00000
	s_mov_b32 s5, 0x42b20000
; #define LAS __attribute__((address_space(3)))
; __device__ __forceinline__ void attn_unit(LAS unsigned char* lds, int unit, int mode, const bf16* QKVG, const float* sinks, const float* gain_a, bf16* MIX, float* SSA) {
;     ...
;         f32x16 st[5];
; #pragma unroll
;         for (int j = 0; j < 5; ++j) {
;             const bool tile_ok = !(nblk == 0 && (i + j) < 4);
;             const float sl = tile_ok ? slope2 : 0.f, bs = tile_ok ? base : -INFINITY;
; #pragma unroll
;             for (int r = 0; r < 16; ++r) st[j][r] = fmaf(sl, (float)((r & 3) + 8 * (r >> 2) + 32 * j), bs);
;         }
;         {
;             const LAS bf16* kp = Ks + (32 * i + q) * KP + hh * 8;
;             bf16x8 kf[2][5];
; #pragma unroll
;             for (int j = 0; j < 5; ++j) kf[0][j] = *(const LAS bf16x8*)(kp + j * 32 * KP);
; #pragma unroll
;             for (int s = 0; s < 4; ++s) {
;                 if (s < 3) {
; #pragma unroll
;                     for (int j = 0; j < 5; ++j) kf[(s + 1) & 1][j] = *(const LAS bf16x8*)(kp + j * 32 * KP + 16 * (s + 1));
;                 }
; #pragma unroll
;                 for (int j = 0; j < 5; ++j) st[j] = __builtin_amdgcn_mfma_f32_32x32x16_bf16(kf[s & 1][j], qr[s], st[j], 0, 0, 0);
;             }
;         }
;         const float sinkq = fmaf(slope2, (float)(128 + 4 * hh) + (float)qq, sink2);
	v_pk_fma_f32 v[28:29], v[0:1], s[4:5], v[2:3] op_sel_hi:[0,1,0]
	s_mov_b32 s4, 0x42a40000
	s_mov_b32 s5, 0x42a60000
	v_pk_fma_f32 v[26:27], v[0:1], s[4:5], v[2:3] op_sel_hi:[0,1,0]
	s_mov_b32 s4, 0x42a00000
	s_mov_b32 s5, 0x42a20000
	v_pk_fma_f32 v[24:25], v[0:1], s[4:5], v[2:3] op_sel_hi:[0,1,0]
	s_mov_b32 s4, 0x42940000
	s_mov_b32 s5, 0x42960000
	v_pk_fma_f32 v[22:23], v[0:1], s[4:5], v[2:3] op_sel_hi:[0,1,0]
	s_mov_b32 s4, 0x42900000
	s_mov_b32 s5, 0x42920000
	s_or_b32 s0, s12, s18
	v_pk_fma_f32 v[20:21], v[0:1], s[4:5], v[2:3] op_sel_hi:[0,1,0]
	s_mov_b32 s4, 0x42840000
	s_cmp_eq_u32 s0, 0
	s_mov_b32 s5, 0x42860000
	v_pk_fma_f32 v[16:17], v[0:1], s[2:3], v[2:3] op_sel_hi:[0,1,0]
	s_cselect_b64 vcc, -1, 0
	s_mov_b32 s2, 0x42f40000
	v_pk_fma_f32 v[18:19], v[0:1], s[4:5], v[2:3] op_sel_hi:[0,1,0]
	v_cndmask_b32_e64 v0, v132, 0, vcc
	v_cndmask_b32_e32 v70, v64, v146, vcc
	s_mov_b32 s3, 0x42f60000
	v_pk_fma_f32 v[14:15], v[0:1], s[2:3], v[70:71] op_sel_hi:[0,1,0]
	s_mov_b32 s2, 0x42f00000
	s_mov_b32 s3, 0x42f20000
	v_pk_fma_f32 v[12:13], v[0:1], s[2:3], v[70:71] op_sel_hi:[0,1,0]
	s_mov_b32 s2, 0x42e40000
	s_mov_b32 s3, 0x42e60000
	v_pk_fma_f32 v[10:11], v[0:1], s[2:3], v[70:71] op_sel_hi:[0,1,0]
	s_mov_b32 s2, 0x42e00000
	s_mov_b32 s3, 0x42e20000
	v_pk_fma_f32 v[8:9], v[0:1], s[2:3], v[70:71] op_sel_hi:[0,1,0]
	s_mov_b32 s2, 0x42d40000
	s_mov_b32 s3, 0x42d60000
	v_pk_fma_f32 v[6:7], v[0:1], s[2:3], v[70:71] op_sel_hi:[0,1,0]
	s_mov_b32 s2, 0x42d00000
	s_mov_b32 s3, 0x42d20000
	v_pk_fma_f32 v[4:5], v[0:1], s[2:3], v[70:71] op_sel_hi:[0,1,0]
	s_mov_b32 s2, 0x42c40000
	s_mov_b32 s3, 0x42c60000
	v_pk_fma_f32 v[2:3], v[0:1], s[2:3], v[70:71] op_sel_hi:[0,1,0]
	v_or_b32_e32 v1, s15, v134
	s_movk_i32 s0, 0x90
	v_mad_u32_u24 v147, v1, s0, v138
	s_mov_b32 s2, 0x42c00000
	ds_read_b128 v[66:69], v147
	s_mov_b32 s3, 0x42c20000
	v_pk_fma_f32 v[0:1], v[0:1], s[2:3], v[70:71] op_sel_hi:[0,1,0]
	s_mov_b32 s2, 0x431a0000
	s_mov_b32 s3, 0x431b0000
	v_pk_fma_f32 v[78:79], v[132:133], s[2:3], v[64:65] op_sel_hi:[0,1,0]
	s_mov_b32 s2, 0x43180000
	s_mov_b32 s3, 0x43190000
	ds_read_b128 v[70:73], v147 offset:4608
	ds_read_b128 v[142:145], v147 offset:32
	v_pk_fma_f32 v[76:77], v[132:133], s[2:3], v[64:65] op_sel_hi:[0,1,0]
	s_mov_b32 s2, 0x43120000
	s_mov_b32 s3, 0x43130000
	v_pk_fma_f32 v[74:75], v[132:133], s[2:3], v[64:65] op_sel_hi:[0,1,0]
	s_mov_b32 s2, 0x43100000
	s_mov_b32 s3, 0x43110000
	s_waitcnt lgkmcnt(2)
	v_mfma_f32_32x32x16_bf16 v[48:63], v[66:69], v[126:129], v[48:63]
	ds_read_b128 v[66:69], v147 offset:9216
	ds_read_b128 v[150:153], v147 offset:4640
	ds_read_b128 v[154:157], v147 offset:13824
	ds_read_b128 v[172:175], v147 offset:9248
	ds_read_b128 v[176:179], v147 offset:18432
	ds_read_b128 v[180:183], v147 offset:13856
	v_cmp_gt_i32_e32 vcc, 0, v140
	s_lshl_b32 s0, s12, 6
	v_readlane_b32 s43, v253, 11
	v_readlane_b32 s50, v253, 18
	s_waitcnt lgkmcnt(7)
	v_mfma_f32_32x32x16_bf16 v[32:47], v[70:73], v[126:129], v[32:47]
	v_fma_f32 v72, v132, s2, v64
	v_fma_f32 v73, v132, s3, v64
	s_mov_b32 s2, 0x430a0000
	s_mov_b32 s3, 0x430b0000
	v_fma_f32 v70, v132, s2, v64
	v_fma_f32 v71, v132, s3, v64
	s_mov_b32 s2, 0x43080000
	s_mov_b32 s3, 0x43090000
	v_readlane_b32 s51, v253, 19
	s_waitcnt lgkmcnt(5)
	v_mfma_f32_32x32x16_bf16 v[16:31], v[66:69], v[126:129], v[16:31]
	v_fma_f32 v68, v132, s2, v64
	v_fma_f32 v69, v132, s3, v64
	s_mov_b32 s2, 0x43020000
	s_mov_b32 s3, 0x43030000
	v_fma_f32 v66, v132, s2, v64
	v_fma_f32 v67, v132, s3, v64
	s_mov_b32 s2, 0x43000000
	s_mov_b32 s3, 0x43010000
	v_pk_fma_f32 v[64:65], v[132:133], s[2:3], v[64:65] op_sel_hi:[0,1,0]
	s_waitcnt lgkmcnt(3)
	v_mfma_f32_32x32x16_bf16 v[0:15], v[154:157], v[126:129], v[0:15]
	ds_read_b128 v[154:157], v147 offset:18464
	s_movk_i32 s2, 0x80
	s_mov_b64 s[26:27], s[46:47]
	s_waitcnt lgkmcnt(2)
	v_mfma_f32_32x32x16_bf16 v[64:79], v[176:179], v[126:129], v[64:79]
	v_mfma_f32_32x32x16_bf16 v[48:63], v[142:145], v[122:125], v[48:63]
	v_mfma_f32_32x32x16_bf16 v[32:47], v[150:153], v[122:125], v[32:47]
	v_mfma_f32_32x32x16_bf16 v[16:31], v[172:175], v[122:125], v[16:31]
	s_waitcnt lgkmcnt(1)
	v_mfma_f32_32x32x16_bf16 v[0:15], v[180:183], v[122:125], v[0:15]
	s_waitcnt lgkmcnt(0)
	v_mfma_f32_32x32x16_bf16 v[64:79], v[154:157], v[122:125], v[64:79]
	ds_read_b128 v[122:125], v147 offset:64
	ds_read_b128 v[126:129], v147 offset:96
	s_waitcnt lgkmcnt(1)
	v_mfma_f32_32x32x16_bf16 v[48:63], v[122:125], v[118:121], v[48:63]
	ds_read_b128 v[122:125], v147 offset:4672
	ds_read_b128 v[142:145], v147 offset:4704
	s_waitcnt lgkmcnt(1)
	v_mfma_f32_32x32x16_bf16 v[32:47], v[122:125], v[118:121], v[32:47]
	ds_read_b128 v[122:125], v147 offset:9280
	ds_read_b128 v[150:153], v147 offset:9312
	s_waitcnt lgkmcnt(1)
	v_mfma_f32_32x32x16_bf16 v[16:31], v[122:125], v[118:121], v[16:31]
	ds_read_b128 v[122:125], v147 offset:13888
	ds_read_b128 v[154:157], v147 offset:13920
	s_waitcnt lgkmcnt(1)
	v_mfma_f32_32x32x16_bf16 v[0:15], v[122:125], v[118:121], v[0:15]
	ds_read_b128 v[122:125], v147 offset:18496
	ds_read_b128 v[172:175], v147 offset:18528
	s_waitcnt lgkmcnt(1)
	v_mfma_f32_32x32x16_bf16 v[64:79], v[122:125], v[118:121], v[64:79]
	v_or_b32_e32 v119, 0x80, v135
	v_cvt_f32_u32_e32 v119, v119
	v_cvt_f32_i32_e32 v120, v140
	s_waitcnt vmcnt(8)
	v_mul_f32_e32 v118, 0x3fb8aa3b, v141
	v_add_f32_e32 v120, v119, v120
	v_mfma_f32_32x32x16_bf16 v[48:63], v[126:129], v[114:117], v[48:63]
	v_fmac_f32_e32 v118, v132, v120
	s_waitcnt lgkmcnt(0)
; __device__ __forceinline__ void attn_unit(LAS unsigned char* lds, int unit, int mode, const bf16* QKVG, const float* sinks, const float* gain_a, bf16* MIX, float* SSA) {
;     ...
;         const float sinkq = fmaf(slope2, (float)(128 + 4 * hh) + (float)qq, sink2);
;         float mx = sinkq;
; #pragma unroll
;         for (int r = 0; r < 16; ++r) {
;             const int cr = (r & 3) + 8 * (r >> 2);
;             const bool up = cr > qq;
;             st[0][r] = up ? st[0][r] : -INFINITY;
;             st[4][r] = up ? -INFINITY : st[4][r];
;         }
; #pragma unroll
;         for (int j = 0; j < 5; ++j)
; #pragma unroll
;             for (int r = 0; r < 16; ++r) mx = fmaxf(mx, st[j][r]);
;         mx = fmaxf(mx, __shfl_xor(mx, 32));
;         float sum = 0.f;
; #pragma unroll
;         for (int j = 0; j < 5; ++j)
; #pragma unroll
;             for (int r = 0; r < 16; ++r) { const float p = __builtin_amdgcn_exp2f(st[j][r] - mx); st[j][r] = p; sum += p; }
;         sum += __shfl_xor(sum, 32);
;         sum += __builtin_amdgcn_exp2f(sinkq - mx);
	v_mfma_f32_32x32x16_bf16 v[64:79], v[172:175], v[114:117], v[64:79]
	s_nop 8
	v_cndmask_b32_e32 v121, v146, v48, vcc
	v_mfma_f32_32x32x16_bf16 v[32:47], v[142:145], v[114:117], v[32:47]
	s_nop 0
	v_cndmask_b32_e32 v119, v64, v146, vcc
	v_cmp_gt_i32_e32 vcc, 1, v140
	s_nop 1
	v_cndmask_b32_e32 v122, v146, v49, vcc
	v_max3_f32 v48, v118, v121, v122
	v_mfma_f32_32x32x16_bf16 v[16:31], v[150:153], v[114:117], v[16:31]
	v_mfma_f32_32x32x16_bf16 v[0:15], v[154:157], v[114:117], v[0:15]
	v_cndmask_b32_e32 v115, v65, v146, vcc
	v_cmp_gt_i32_e32 vcc, 2, v140
	s_nop 1
	v_cndmask_b32_e32 v123, v146, v50, vcc
	v_cndmask_b32_e32 v116, v66, v146, vcc
	v_cmp_gt_i32_e32 vcc, 3, v140
	s_nop 1
	v_cndmask_b32_e32 v124, v146, v51, vcc
	v_cndmask_b32_e32 v117, v67, v146, vcc
	v_cmp_gt_i32_e32 vcc, 8, v140
	v_max3_f32 v48, v48, v123, v124
	s_nop 0
	v_cndmask_b32_e32 v125, v146, v52, vcc
	v_cndmask_b32_e32 v114, v68, v146, vcc
	v_cmp_gt_i32_e32 vcc, 9, v140
	s_nop 1
	v_cndmask_b32_e32 v126, v146, v53, vcc
	v_cndmask_b32_e32 v68, v69, v146, vcc
	v_cmp_gt_i32_e32 vcc, 10, v140
	v_max3_f32 v48, v48, v125, v126
	s_nop 0
	v_cndmask_b32_e32 v69, v146, v54, vcc
	v_cndmask_b32_e32 v67, v70, v146, vcc
	v_cmp_gt_i32_e32 vcc, 11, v140
	s_nop 1
	v_cndmask_b32_e32 v70, v146, v55, vcc
	v_cndmask_b32_e32 v65, v71, v146, vcc
	v_cmp_gt_i32_e32 vcc, 16, v140
	v_max3_f32 v48, v48, v69, v70
	s_nop 0
	v_cndmask_b32_e32 v71, v146, v56, vcc
	v_cndmask_b32_e32 v66, v72, v146, vcc
	v_cmp_gt_i32_e32 vcc, 17, v140
	s_nop 1
	v_cndmask_b32_e32 v72, v146, v57, vcc
	v_cndmask_b32_e32 v64, v73, v146, vcc
	v_cmp_gt_i32_e32 vcc, 18, v140
	v_max3_f32 v48, v48, v71, v72
	s_nop 0
	v_cndmask_b32_e32 v73, v146, v58, vcc
	v_cndmask_b32_e32 v57, v74, v146, vcc
	v_cmp_gt_i32_e32 vcc, 19, v140
	s_nop 1
	v_cndmask_b32_e32 v59, v146, v59, vcc
	v_cndmask_b32_e32 v56, v75, v146, vcc
	v_cmp_gt_i32_e32 vcc, 24, v140
	v_max3_f32 v48, v48, v73, v59
	v_mul_u32_u24_e32 v75, 0x210, v134
	v_cndmask_b32_e32 v60, v146, v60, vcc
	v_cndmask_b32_e32 v53, v76, v146, vcc
	v_cmp_gt_i32_e32 vcc, 25, v140
	s_nop 1
	v_cndmask_b32_e32 v61, v146, v61, vcc
	v_cndmask_b32_e32 v54, v77, v146, vcc
	v_cmp_gt_i32_e32 vcc, 26, v140
	v_max3_f32 v48, v48, v60, v61
	s_nop 0
	v_cndmask_b32_e32 v62, v146, v62, vcc
	v_cndmask_b32_e32 v55, v78, v146, vcc
	v_cmp_gt_i32_e32 vcc, 27, v140
	s_nop 1
	v_cndmask_b32_e32 v63, v146, v63, vcc
	v_max3_f32 v48, v48, v62, v63
	v_max3_f32 v48, v48, v32, v33
	v_max3_f32 v48, v48, v34, v35
	v_max3_f32 v48, v48, v36, v37
	v_max3_f32 v48, v48, v38, v39
	v_max3_f32 v48, v48, v40, v41
	v_max3_f32 v48, v48, v42, v43
	v_max3_f32 v48, v48, v44, v45
	v_max3_f32 v48, v48, v46, v47
	v_max3_f32 v48, v48, v16, v17
	v_max3_f32 v48, v48, v18, v19
	v_max3_f32 v48, v48, v20, v21
	v_max3_f32 v48, v48, v22, v23
	v_max3_f32 v48, v48, v24, v25
	v_max3_f32 v48, v48, v26, v27
	v_max3_f32 v48, v48, v28, v29
	v_max3_f32 v48, v48, v30, v31
	v_max3_f32 v48, v48, v0, v1
	v_max3_f32 v48, v48, v2, v3
	v_max3_f32 v48, v48, v4, v5
	v_max3_f32 v48, v48, v6, v7
	v_max3_f32 v48, v48, v8, v9
	v_max3_f32 v48, v48, v10, v11
	v_max3_f32 v48, v48, v12, v13
	v_max3_f32 v48, v48, v14, v15
	v_max3_f32 v48, v48, v119, v115
	v_max3_f32 v48, v48, v116, v117
	v_max3_f32 v48, v48, v114, v68
	v_max3_f32 v48, v48, v67, v65
	v_max3_f32 v48, v48, v66, v64
	v_max3_f32 v48, v48, v57, v56
	v_cndmask_b32_e32 v52, v79, v146, vcc
	v_max3_f32 v48, v48, v53, v54
	v_max3_f32 v51, v48, v55, v52
	v_mbcnt_lo_u32_b32 v48, -1, 0
	v_mbcnt_hi_u32_b32 v49, -1, v48
	v_and_b32_e32 v50, 64, v49
	v_xor_b32_e32 v48, 32, v49
	v_add_u32_e32 v50, 64, v50
	v_cmp_lt_i32_e32 vcc, v48, v50
	s_nop 1
	v_cndmask_b32_e32 v48, v49, v48, vcc
	v_lshlrev_b32_e32 v48, 2, v48
	ds_bpermute_b32 v58, v48, v51
	v_cmp_gt_u32_e32 vcc, 32, v231
	s_waitcnt lgkmcnt(0)
	v_max_f32_e32 v58, v58, v58
	v_max_f32_e32 v58, v51, v58
	v_sub_f32_e32 v51, v121, v58
	v_exp_f32_e32 v74, v51
	v_sub_f32_e32 v77, v122, v58
	v_exp_f32_e32 v77, v77
	v_sub_f32_e32 v78, v123, v58
	v_exp_f32_e32 v78, v78
	v_sub_f32_e32 v79, v124, v58
	v_exp_f32_e32 v79, v79
	v_sub_f32_e32 v120, v125, v58
	v_add_f32_e32 v76, 0, v74
	v_exp_f32_e32 v120, v120
	v_sub_f32_e32 v121, v126, v58
	v_add_f32_e32 v76, v77, v76
	v_exp_f32_e32 v121, v121
	v_sub_f32_e32 v69, v69, v58
	v_add_f32_e32 v76, v78, v76
	v_exp_f32_e32 v69, v69
	v_sub_f32_e32 v70, v70, v58
	v_add_f32_e32 v76, v79, v76
	v_exp_f32_e32 v70, v70
	v_sub_f32_e32 v71, v71, v58
	v_add_f32_e32 v76, v120, v76
	v_exp_f32_e32 v71, v71
	v_sub_f32_e32 v72, v72, v58
	v_add_f32_e32 v76, v121, v76
	v_exp_f32_e32 v72, v72
	v_sub_f32_e32 v73, v73, v58
	v_add_f32_e32 v76, v69, v76
	v_exp_f32_e32 v73, v73
	v_sub_f32_e32 v59, v59, v58
	v_add_f32_e32 v76, v70, v76
	v_exp_f32_e32 v59, v59
	v_sub_f32_e32 v60, v60, v58
	v_add_f32_e32 v76, v71, v76
	v_exp_f32_e32 v60, v60
	v_sub_f32_e32 v61, v61, v58
	v_add_f32_e32 v76, v72, v76
	v_exp_f32_e32 v61, v61
	v_sub_f32_e32 v62, v62, v58
	v_add_f32_e32 v76, v73, v76
	v_exp_f32_e32 v62, v62
	v_sub_f32_e32 v63, v63, v58
	v_add_f32_e32 v76, v59, v76
	v_exp_f32_e32 v63, v63
	v_sub_f32_e32 v32, v32, v58
	v_add_f32_e32 v76, v60, v76
	v_exp_f32_e32 v122, v32
	v_sub_f32_e32 v33, v33, v58
	v_add_f32_e32 v32, v61, v76
	v_exp_f32_e32 v76, v33
	v_sub_f32_e32 v33, v34, v58
	v_add_f32_e32 v32, v62, v32
	v_exp_f32_e32 v123, v33
	v_sub_f32_e32 v33, v35, v58
	v_add_f32_e32 v32, v63, v32
	v_exp_f32_e32 v124, v33
	v_sub_f32_e32 v33, v36, v58
	v_add_f32_e32 v32, v122, v32
	v_exp_f32_e32 v125, v33
	v_sub_f32_e32 v33, v37, v58
	v_add_f32_e32 v32, v76, v32
	v_exp_f32_e32 v126, v33
	v_sub_f32_e32 v33, v38, v58
	v_add_f32_e32 v32, v123, v32
	v_exp_f32_e32 v127, v33
	v_sub_f32_e32 v33, v39, v58
; #define LAS __attribute__((address_space(3)))
; __device__ __forceinline__ unsigned pk2(float lo, float hi) { return pg8::cvt_pk_bf16(lo, hi); }
; __device__ __forceinline__ void attn_unit(LAS unsigned char* lds, int unit, int mode, const bf16* QKVG, const float* sinks, const float* gain_a, bf16* MIX, float* SSA) {
;     ...
;         for (int j = 0; j < 5; ++j)
; #pragma unroll
;             for (int r = 0; r < 16; ++r) { const float p = __builtin_amdgcn_exp2f(st[j][r] - mx); st[j][r] = p; sum += p; }
;         sum += __shfl_xor(sum, 32);
;         sum += __builtin_amdgcn_exp2f(sinkq - mx);
;         const float inv = __builtin_amdgcn_rcpf(sum);
;         f32x16 ot[2]; ot[0] = f32x16{}; ot[1] = f32x16{};
; #pragma unroll
;         for (int j = 0; j < 5; ++j)
; #pragma unroll
;             for (int s2 = 0; s2 < 2; ++s2) {
;                 v4u pw; pw.x = pk2(st[j][8 * s2 + 0], st[j][8 * s2 + 1]); pw.y = pk2(st[j][8 * s2 + 2], st[j][8 * s2 + 3]);
;                 pw.z = pk2(st[j][8 * s2 + 4], st[j][8 * s2 + 5]); pw.w = pk2(st[j][8 * s2 + 6], st[j][8 * s2 + 7]);
;                 const bf16x8 pf = __builtin_bit_cast(bf16x8, pw);
; #pragma unroll
;                 for (int db = 0; db < 2; ++db) {
;                     const bf16x8 vf = *(const LAS bf16x8*)(Vt + (db * 32 + q) * VP + 32 * (i + j) + 16 * s2 + 8 * hh);
;                     ot[db] = __builtin_amdgcn_mfma_f32_32x32x16_bf16(vf, pf, ot[db], 0, 0, 0);
;                 }
;             }
	v_add_f32_e32 v32, v124, v32
	v_exp_f32_e32 v128, v33
	v_sub_f32_e32 v33, v40, v58
	v_add_f32_e32 v32, v125, v32
	v_exp_f32_e32 v129, v33
	v_sub_f32_e32 v33, v41, v58
	v_add_f32_e32 v32, v126, v32
	v_exp_f32_e32 v132, v33
	v_sub_f32_e32 v33, v42, v58
	v_lshl_add_u32 v51, v135, 1, v139
	v_add_f32_e32 v32, v127, v32
	v_exp_f32_e32 v139, v33
	v_sub_f32_e32 v33, v43, v58
	v_add_f32_e32 v32, v128, v32
	v_exp_f32_e32 v140, v33
	v_sub_f32_e32 v33, v44, v58
	v_add_f32_e32 v32, v129, v32
	v_exp_f32_e32 v141, v33
	v_sub_f32_e32 v33, v45, v58
	v_add_f32_e32 v32, v132, v32
	v_exp_f32_e32 v142, v33
	v_sub_f32_e32 v33, v46, v58
	v_add_f32_e32 v32, v139, v32
	v_exp_f32_e32 v143, v33
	v_sub_f32_e32 v33, v47, v58
	v_add_f32_e32 v32, v140, v32
	v_exp_f32_e32 v144, v33
	v_sub_f32_e32 v16, v16, v58
	v_add_f32_e32 v32, v141, v32
	v_exp_f32_e32 v145, v16
	v_sub_f32_e32 v17, v17, v58
	v_add_f32_e32 v16, v142, v32
	v_exp_f32_e32 v146, v17
	v_sub_f32_e32 v17, v18, v58
	v_add_f32_e32 v16, v143, v16
	v_exp_f32_e32 v147, v17
	v_sub_f32_e32 v17, v19, v58
	v_add_f32_e32 v16, v144, v16
	v_exp_f32_e32 v148, v17
	v_sub_f32_e32 v17, v20, v58
	v_add_f32_e32 v16, v145, v16
	v_exp_f32_e32 v150, v17
	v_sub_f32_e32 v17, v21, v58
	v_add_f32_e32 v16, v146, v16
	v_exp_f32_e32 v151, v17
	v_sub_f32_e32 v17, v22, v58
	v_add_f32_e32 v16, v147, v16
	v_exp_f32_e32 v152, v17
	v_sub_f32_e32 v17, v23, v58
	v_add_f32_e32 v16, v148, v16
	v_exp_f32_e32 v153, v17
	v_sub_f32_e32 v17, v24, v58
	v_add_f32_e32 v16, v150, v16
	v_exp_f32_e32 v154, v17
	v_sub_f32_e32 v17, v25, v58
	v_add_f32_e32 v16, v151, v16
	v_exp_f32_e32 v155, v17
	v_sub_f32_e32 v17, v26, v58
	v_add_f32_e32 v16, v152, v16
	v_exp_f32_e32 v156, v17
	v_sub_f32_e32 v17, v27, v58
	v_add_f32_e32 v16, v153, v16
	v_exp_f32_e32 v157, v17
	v_sub_f32_e32 v17, v28, v58
	v_add_f32_e32 v16, v154, v16
	v_exp_f32_e32 v158, v17
	v_sub_f32_e32 v17, v29, v58
	v_add_f32_e32 v16, v155, v16
	v_exp_f32_e32 v159, v17
	v_sub_f32_e32 v17, v30, v58
	v_add_f32_e32 v16, v156, v16
	v_exp_f32_e32 v172, v17
	v_sub_f32_e32 v17, v31, v58
	v_add_f32_e32 v16, v157, v16
	v_exp_f32_e32 v173, v17
	v_sub_f32_e32 v0, v0, v58
	v_add_f32_e32 v16, v158, v16
	v_exp_f32_e32 v174, v0
	v_sub_f32_e32 v1, v1, v58
	v_add_f32_e32 v0, v159, v16
	v_exp_f32_e32 v175, v1
	v_sub_f32_e32 v1, v2, v58
	v_add_f32_e32 v0, v172, v0
	v_exp_f32_e32 v176, v1
	v_sub_f32_e32 v1, v3, v58
	v_add_f32_e32 v0, v173, v0
	v_exp_f32_e32 v177, v1
	v_sub_f32_e32 v1, v4, v58
	v_add_f32_e32 v0, v174, v0
	v_exp_f32_e32 v178, v1
	v_add_f32_e32 v0, v175, v0
	v_add_f32_e32 v0, v176, v0
	v_add_f32_e32 v0, v177, v0
	v_add_f32_e32 v16, v178, v0
	v_sub_f32_e32 v0, v5, v58
	v_exp_f32_e32 v179, v0
	v_sub_f32_e32 v0, v6, v58
	v_exp_f32_e32 v180, v0
	v_sub_f32_e32 v17, v7, v58
	v_cvt_pk_bf16_f32 v0, v74, v77
	v_cvt_pk_bf16_f32 v1, v78, v79
	v_cvt_pk_bf16_f32 v2, v120, v121
	v_cvt_pk_bf16_f32 v3, v69, v70
	v_add3_u32 v69, v138, s0, v75
	v_sub_f32_e32 v8, v8, v58
	ds_read_b128 v[4:7], v69 offset:36864
	v_exp_f32_e32 v70, v17
	v_exp_f32_e32 v74, v8
	v_add_f32_e32 v8, v179, v16
	ds_read_b128 v[16:19], v69 offset:53760
	s_waitcnt lgkmcnt(1)
	v_mfma_f32_32x32x16_bf16 v[32:47], v[4:7], v[0:3], 0
	v_sub_f32_e32 v4, v9, v58
	v_exp_f32_e32 v78, v4
	v_cvt_pk_bf16_f32 v4, v71, v72
	v_cvt_pk_bf16_f32 v5, v73, v59
	v_cvt_pk_bf16_f32 v6, v60, v61
	v_cvt_pk_bf16_f32 v7, v62, v63
	ds_read_b128 v[60:63], v69 offset:36896
	s_waitcnt lgkmcnt(1)
	v_mfma_f32_32x32x16_bf16 v[16:31], v[16:19], v[0:3], 0
	v_sub_f32_e32 v0, v10, v58
	v_exp_f32_e32 v59, v0
	v_sub_f32_e32 v0, v11, v58
	v_exp_f32_e32 v71, v0
	v_sub_f32_e32 v0, v12, v58
	v_exp_f32_e32 v72, v0
	ds_read_b128 v[0:3], v69 offset:53792
	v_add_f32_e32 v8, v180, v8
	v_add_f32_e32 v8, v70, v8
	v_add_f32_e32 v77, v74, v8
	s_waitcnt lgkmcnt(0)
	v_mfma_f32_32x32x16_bf16 v[16:31], v[0:3], v[4:7], v[16:31]
	v_add_f32_e32 v0, v78, v77
	v_add_f32_e32 v0, v59, v0
	s_lshl_b32 s0, s17, 6
	v_add_f32_e32 v0, v71, v0
	v_add3_u32 v12, v138, s0, v75
	v_add_f32_e32 v73, v72, v0
	v_sub_f32_e32 v0, v13, v58
	v_mfma_f32_32x32x16_bf16 v[32:47], v[60:63], v[4:7], v[32:47]
	v_cvt_pk_bf16_f32 v8, v122, v76
	v_cvt_pk_bf16_f32 v9, v123, v124
	v_cvt_pk_bf16_f32 v10, v125, v126
	v_cvt_pk_bf16_f32 v11, v127, v128
	ds_read_b128 v[60:63], v12 offset:36864
	v_exp_f32_e32 v75, v0
	ds_read_b128 v[0:3], v12 offset:53760
	v_sub_f32_e32 v4, v14, v58
	v_exp_f32_e32 v76, v4
	s_waitcnt lgkmcnt(0)
	v_mfma_f32_32x32x16_bf16 v[16:31], v[0:3], v[8:11], v[16:31]
	v_add_f32_e32 v0, v75, v73
	v_cvt_pk_bf16_f32 v4, v129, v132
	v_cvt_pk_bf16_f32 v5, v139, v140
	v_cvt_pk_bf16_f32 v6, v141, v142
	v_cvt_pk_bf16_f32 v7, v143, v144
	v_add_u32_e32 v132, s15, v136
	s_lshl_b32 s0, s14, 1
	v_mfma_f32_32x32x16_bf16 v[32:47], v[60:63], v[8:11], v[32:47]
	v_add_f32_e32 v8, v76, v0
	v_sub_f32_e32 v0, v15, v58
	v_exp_f32_e32 v73, v0
	v_sub_f32_e32 v0, v119, v58
	ds_read_b128 v[60:63], v12 offset:36896
	v_exp_f32_e32 v77, v0
	ds_read_b128 v[0:3], v12 offset:53792
	s_waitcnt lgkmcnt(0)
	v_mfma_f32_32x32x16_bf16 v[16:31], v[0:3], v[4:7], v[16:31]
	v_sub_f32_e32 v0, v115, v58
	v_add_f32_e32 v8, v73, v8
	v_mfma_f32_32x32x16_bf16 v[32:47], v[60:63], v[4:7], v[32:47]
	v_exp_f32_e32 v61, v0
	v_sub_f32_e32 v0, v116, v58
	v_exp_f32_e32 v62, v0
	v_sub_f32_e32 v0, v117, v58
	v_add_f32_e32 v60, v77, v8
	v_cvt_pk_bf16_f32 v8, v145, v146
	v_cvt_pk_bf16_f32 v9, v147, v148
	v_cvt_pk_bf16_f32 v10, v150, v151
	v_cvt_pk_bf16_f32 v11, v152, v153
	ds_read_b128 v[12:15], v69 offset:36992
	v_exp_f32_e32 v63, v0
	ds_read_b128 v[0:3], v69 offset:53888
	v_sub_f32_e32 v4, v114, v58
	v_exp_f32_e32 v79, v4
	s_waitcnt lgkmcnt(0)
; #define LAS __attribute__((address_space(3)))
; __device__ __forceinline__ unsigned pk2(float lo, float hi) { return pg8::cvt_pk_bf16(lo, hi); }
; __device__ __forceinline__ float bflo(unsigned w) { return __uint_as_float(w << 16); }
; __device__ __forceinline__ float bfhi(unsigned w) { return __uint_as_float(w & 0xffff0000u); }
; __device__ __forceinline__ float silu(float g) { return g * __builtin_amdgcn_rcpf(1.0f + __builtin_amdgcn_exp2f(-1.4426950408889634f * g)); }
; __device__ __forceinline__ void attn_unit(LAS unsigned char* lds, int unit, int mode, const bf16* QKVG, const float* sinks, const float* gain_a, bf16* MIX, float* SSA) {
;     ...
;         f32x16 ot[2]; ot[0] = f32x16{}; ot[1] = f32x16{};
; #pragma unroll
;         for (int j = 0; j < 5; ++j)
; #pragma unroll
;             for (int s2 = 0; s2 < 2; ++s2) {
;                 v4u pw; pw.x = pk2(st[j][8 * s2 + 0], st[j][8 * s2 + 1]); pw.y = pk2(st[j][8 * s2 + 2], st[j][8 * s2 + 3]);
;                 pw.z = pk2(st[j][8 * s2 + 4], st[j][8 * s2 + 5]); pw.w = pk2(st[j][8 * s2 + 6], st[j][8 * s2 + 7]);
;                 const bf16x8 pf = __builtin_bit_cast(bf16x8, pw);
; #pragma unroll
;                 for (int db = 0; db < 2; ++db) {
;                     const bf16x8 vf = *(const LAS bf16x8*)(Vt + (db * 32 + q) * VP + 32 * (i + j) + 16 * s2 + 8 * hh);
;                     ot[db] = __builtin_amdgcn_mfma_f32_32x32x16_bf16(vf, pf, ot[db], 0, 0, 0);
;                 }
;             }
;         float ss = 0.f;
; #pragma unroll
;         for (int k = 0; k < 4; ++k) *(LAS v4u*)(wt_row + 8 * k * KP) = grow[k];
; #pragma unroll
;         for (int e = 0; e < 8; ++e) gt[e] = *(const LAS v2u*)(wt_frd + 32 * (e >> 2) + 8 * (e & 3));
; #pragma unroll
;         for (int e = 0; e < 8; ++e) {
;             const int db = e >> 2, g4 = e & 3;
;             const float o0 = ot[db][4 * g4 + 0] * inv, o1 = ot[db][4 * g4 + 1] * inv, o2 = ot[db][4 * g4 + 2] * inv, o3 = ot[db][4 * g4 + 3] * inv;
;             ss += (o0 * o0 + o1 * o1) + (o2 * o2 + o3 * o3);
;             const f32x4 gn = *(const LAS f32x4*)(GN + 4 * hh + 32 * db + 8 * g4);
;             v2u z; z.x = pk2(o0 * gn[0] * silu(bflo(gt[e].x)), o1 * gn[1] * silu(bfhi(gt[e].x)));
;             z.y = pk2(o2 * gn[2] * silu(bflo(gt[e].y)), o3 * gn[3] * silu(bfhi(gt[e].y)));
;             *(LAS v2u*)(wt_frd + 32 * db + 8 * g4) = z;
;         }
	v_mfma_f32_32x32x16_bf16 v[16:31], v[0:3], v[8:11], v[16:31]
	v_add_f32_e32 v0, v61, v60
	v_add_f32_e32 v0, v62, v0
	v_add_f32_e32 v0, v63, v0
	v_add_f32_e32 v60, v79, v0
	v_sub_f32_e32 v0, v68, v58
	v_cvt_pk_bf16_f32 v4, v154, v155
	v_cvt_pk_bf16_f32 v5, v156, v157
	v_mfma_f32_32x32x16_bf16 v[32:47], v[12:15], v[8:11], v[32:47]
	v_cvt_pk_bf16_f32 v6, v158, v159
	v_cvt_pk_bf16_f32 v7, v172, v173
	ds_read_b128 v[12:15], v69 offset:37024
	v_exp_f32_e32 v68, v0
	ds_read_b128 v[0:3], v69 offset:53920
	v_sub_f32_e32 v8, v67, v58
	v_exp_f32_e32 v67, v8
	s_waitcnt lgkmcnt(0)
	v_mfma_f32_32x32x16_bf16 v[16:31], v[0:3], v[4:7], v[16:31]
	v_add_f32_e32 v0, v68, v60
	v_add_f32_e32 v60, v67, v0
	v_sub_f32_e32 v0, v65, v58
	v_exp_f32_e32 v65, v0
	v_sub_f32_e32 v0, v66, v58
	v_cvt_pk_bf16_f32 v8, v174, v175
	v_cvt_pk_bf16_f32 v9, v176, v177
	v_mfma_f32_32x32x16_bf16 v[32:47], v[12:15], v[4:7], v[32:47]
	v_cvt_pk_bf16_f32 v10, v178, v179
	v_cvt_pk_bf16_f32 v11, v180, v70
	ds_read_b128 v[12:15], v69 offset:37056
	v_exp_f32_e32 v66, v0
	ds_read_b128 v[0:3], v69 offset:53952
	v_sub_f32_e32 v4, v64, v58
	v_exp_f32_e32 v64, v4
	s_waitcnt lgkmcnt(0)
	v_mfma_f32_32x32x16_bf16 v[16:31], v[0:3], v[8:11], v[16:31]
	v_sub_f32_e32 v0, v57, v58
	v_exp_f32_e32 v57, v0
	v_add_f32_e32 v0, v65, v60
	v_add_f32_e32 v0, v66, v0
	v_add_f32_e32 v0, v64, v0
	v_cvt_pk_bf16_f32 v4, v74, v78
	v_cvt_pk_bf16_f32 v5, v59, v71
	v_mfma_f32_32x32x16_bf16 v[32:47], v[12:15], v[8:11], v[32:47]
	v_cvt_pk_bf16_f32 v6, v72, v75
	v_cvt_pk_bf16_f32 v7, v76, v73
	ds_read_b128 v[12:15], v69 offset:37088
	v_add_f32_e32 v59, v57, v0
	ds_read_b128 v[0:3], v69 offset:53984
	v_sub_f32_e32 v8, v56, v58
	v_exp_f32_e32 v56, v8
	s_waitcnt lgkmcnt(0)
	v_mfma_f32_32x32x16_bf16 v[16:31], v[0:3], v[4:7], v[16:31]
	v_sub_f32_e32 v0, v53, v58
	v_exp_f32_e32 v53, v0
	v_sub_f32_e32 v0, v54, v58
	v_exp_f32_e32 v54, v0
	v_sub_f32_e32 v0, v55, v58
	v_cvt_pk_bf16_f32 v8, v77, v61
	v_cvt_pk_bf16_f32 v9, v62, v63
	v_mfma_f32_32x32x16_bf16 v[32:47], v[12:15], v[4:7], v[32:47]
	v_cvt_pk_bf16_f32 v10, v79, v68
	v_cvt_pk_bf16_f32 v11, v67, v65
	ds_read_b128 v[12:15], v69 offset:37120
	v_exp_f32_e32 v55, v0
	ds_read_b128 v[0:3], v69 offset:54016
	v_sub_f32_e32 v4, v52, v58
	v_exp_f32_e32 v52, v4
	s_waitcnt lgkmcnt(0)
	v_mfma_f32_32x32x16_bf16 v[16:31], v[0:3], v[8:11], v[16:31]
	v_add_f32_e32 v0, v56, v59
	v_cvt_pk_bf16_f32 v4, v66, v64
	v_cvt_pk_bf16_f32 v5, v57, v56
	v_cvt_pk_bf16_f32 v6, v53, v54
	v_cvt_pk_bf16_f32 v7, v55, v52
	v_add_f32_e32 v0, v53, v0
	v_add_f32_e32 v0, v54, v0
	v_mfma_f32_32x32x16_bf16 v[32:47], v[12:15], v[8:11], v[32:47]
	ds_read_b128 v[12:15], v69 offset:37152
	v_add_f32_e32 v0, v55, v0
	v_add_f32_e32 v8, v52, v0
	ds_read_b128 v[0:3], v69 offset:54048
	ds_bpermute_b32 v9, v48, v8
	v_sub_f32_e32 v10, v118, v58
	v_exp_f32_e32 v10, v10
	s_waitcnt lgkmcnt(2)
	v_mfma_f32_32x32x16_bf16 v[32:47], v[12:15], v[4:7], v[32:47]
	s_waitcnt lgkmcnt(0)
	v_add_f32_e32 v8, v8, v9
	v_add_f32_e32 v8, v10, v8
	s_waitcnt vmcnt(7)
	ds_write_b128 v137, v[98:101]
	s_waitcnt vmcnt(2)
	ds_write_b128 v137, v[102:105] offset:1152
	s_waitcnt vmcnt(1)
	ds_write_b128 v137, v[106:109] offset:2304
	s_waitcnt vmcnt(0)
	ds_write_b128 v137, v[110:113] offset:3456
	v_rcp_f32_e32 v53, v8
	v_lshl_add_u32 v52, v135, 2, s16
	v_mul_f32_e32 v13, v32, v53
	v_mfma_f32_32x32x16_bf16 v[16:31], v[0:3], v[4:7], v[16:31]
	ds_read2_b64 v[54:57], v51 offset1:2
	ds_read2_b64 v[8:11], v51 offset0:4 offset1:6
	ds_read2_b64 v[4:7], v51 offset0:8 offset1:10
	ds_read2_b64 v[0:3], v51 offset0:12 offset1:14
	v_mul_f32_e32 v59, v33, v53
	s_waitcnt lgkmcnt(3)
	v_lshlrev_b32_e32 v12, 16, v54
	v_mul_f32_e32 v58, 0xbfb8aa3b, v12
	v_exp_f32_e32 v60, v58
	v_and_b32_e32 v58, 0xffff0000, v54
	v_mul_f32_e32 v61, v34, v53
	v_mul_f32_e32 v63, v35, v53
	ds_read_b128 v[32:35], v52
	v_mul_f32_e32 v54, 0xbfb8aa3b, v58
	v_exp_f32_e32 v54, v54
	v_add_f32_e32 v60, 1.0, v60
	v_rcp_f32_e32 v64, v60
	s_waitcnt lgkmcnt(0)
	v_mov_b32_e32 v65, v32
	v_add_f32_e32 v32, 1.0, v54
	v_rcp_f32_e32 v32, v32
	v_lshlrev_b32_e32 v60, 16, v55
	v_and_b32_e32 v62, 0xffff0000, v55
	v_pk_mul_f32 v[64:65], v[64:65], v[12:13]
	v_pk_mul_f32 v[32:33], v[32:33], v[58:59]
	v_mul_f32_e32 v12, v64, v65
	v_mul_f32_e32 v54, v32, v33
	v_mul_f32_e32 v32, 0xbfb8aa3b, v60
	v_exp_f32_e32 v32, v32
	v_mul_f32_e32 v33, 0xbfb8aa3b, v62
	v_exp_f32_e32 v55, v33
	v_mov_b32_e32 v33, v34
	v_add_f32_e32 v32, 1.0, v32
	v_rcp_f32_e32 v32, v32
	v_add_f32_e32 v34, 1.0, v55
	v_rcp_f32_e32 v34, v34
	v_cvt_pk_bf16_f32 v54, v12, v54
	v_pk_mul_f32 v[32:33], v[32:33], v[60:61]
	v_mul_f32_e32 v15, v63, v63
	v_mul_f32_e32 v12, v32, v33
	v_pk_mul_f32 v[32:33], v[34:35], v[62:63]
	v_fmac_f32_e32 v15, v61, v61
	v_mul_f32_e32 v32, v32, v33
	v_cvt_pk_bf16_f32 v55, v12, v32
	ds_write_b64 v51, v[54:55]
	v_lshlrev_b32_e32 v54, 16, v56
	v_mul_f32_e32 v55, v36, v53
	v_mul_f32_e32 v36, 0xbfb8aa3b, v54
	v_exp_f32_e32 v58, v36
	v_and_b32_e32 v36, 0xffff0000, v56
	ds_read_b128 v[32:35], v52 offset:32
	v_mul_f32_e32 v56, 0xbfb8aa3b, v36
	v_exp_f32_e32 v56, v56
	v_mul_f32_e32 v37, v37, v53
	v_mul_f32_e32 v39, v39, v53
	s_waitcnt lgkmcnt(0)
; #define LAS __attribute__((address_space(3)))
; __device__ __forceinline__ unsigned pk2(float lo, float hi) { return pg8::cvt_pk_bf16(lo, hi); }
; __device__ __forceinline__ float bflo(unsigned w) { return __uint_as_float(w << 16); }
; __device__ __forceinline__ float bfhi(unsigned w) { return __uint_as_float(w & 0xffff0000u); }
; __device__ __forceinline__ float silu(float g) { return g * __builtin_amdgcn_rcpf(1.0f + __builtin_amdgcn_exp2f(-1.4426950408889634f * g)); }
; __device__ __forceinline__ void attn_unit(LAS unsigned char* lds, int unit, int mode, const bf16* QKVG, const float* sinks, const float* gain_a, bf16* MIX, float* SSA) {
;     ...
; #pragma unroll
;         for (int e = 0; e < 8; ++e) {
;             const int db = e >> 2, g4 = e & 3;
;             const float o0 = ot[db][4 * g4 + 0] * inv, o1 = ot[db][4 * g4 + 1] * inv, o2 = ot[db][4 * g4 + 2] * inv, o3 = ot[db][4 * g4 + 3] * inv;
;             ss += (o0 * o0 + o1 * o1) + (o2 * o2 + o3 * o3);
;             const f32x4 gn = *(const LAS f32x4*)(GN + 4 * hh + 32 * db + 8 * g4);
;             v2u z; z.x = pk2(o0 * gn[0] * silu(bflo(gt[e].x)), o1 * gn[1] * silu(bfhi(gt[e].x)));
;             z.y = pk2(o2 * gn[2] * silu(bflo(gt[e].y)), o3 * gn[3] * silu(bfhi(gt[e].y)));
;             *(LAS v2u*)(wt_frd + 32 * db + 8 * g4) = z;
;         }
	v_mov_b32_e32 v61, v32
	v_add_f32_e32 v32, 1.0, v56
	v_rcp_f32_e32 v32, v32
	v_mul_f32_e32 v14, v59, v59
	v_mul_f32_e32 v59, v38, v53
	v_mul_f32_e32 v12, v37, v37
	v_mul_f32_e32 v38, v39, v39
	v_add_f32_e32 v58, 1.0, v58
	v_fmac_f32_e32 v12, v55, v55
	v_fmac_f32_e32 v38, v59, v59
	v_rcp_f32_e32 v60, v58
	v_pk_mul_f32 v[32:33], v[32:33], v[36:37]
	v_lshlrev_b32_e32 v58, 16, v57
	v_add_f32_e32 v12, v12, v38
	v_mul_f32_e32 v36, v32, v33
	v_mul_f32_e32 v32, 0xbfb8aa3b, v58
	v_and_b32_e32 v38, 0xffff0000, v57
	v_exp_f32_e32 v32, v32
	v_mul_f32_e32 v33, 0xbfb8aa3b, v38
	v_exp_f32_e32 v37, v33
	v_mov_b32_e32 v33, v34
	v_add_f32_e32 v32, 1.0, v32
	v_rcp_f32_e32 v32, v32
	v_add_f32_e32 v34, 1.0, v37
	v_rcp_f32_e32 v34, v34
	v_pk_mul_f32 v[54:55], v[60:61], v[54:55]
	v_pk_mul_f32 v[32:33], v[32:33], v[58:59]
	v_mul_f32_e32 v54, v54, v55
	v_cvt_pk_bf16_f32 v36, v54, v36
	v_mul_f32_e32 v37, v32, v33
	v_pk_mul_f32 v[32:33], v[34:35], v[38:39]
	v_mul_f32_e32 v39, v41, v53
	v_mul_f32_e32 v32, v32, v33
	v_cvt_pk_bf16_f32 v37, v37, v32
	ds_write_b64 v51, v[36:37] offset:16
	v_lshlrev_b32_e32 v36, 16, v8
	v_mul_f32_e32 v38, 0xbfb8aa3b, v36
	v_exp_f32_e32 v54, v38
	v_and_b32_e32 v38, 0xffff0000, v8
	v_mul_f32_e32 v8, 0xbfb8aa3b, v38
	ds_read_b128 v[32:35], v52 offset:64
	v_exp_f32_e32 v8, v8
	v_mul_f32_e32 v43, v43, v53
	v_mul_f32_e32 v37, v40, v53
	v_mul_f32_e32 v41, v42, v53
	v_add_f32_e32 v8, 1.0, v8
	v_mul_f32_e32 v40, v39, v39
	v_mul_f32_e32 v42, v43, v43
	s_waitcnt lgkmcnt(0)
	v_mov_b32_e32 v55, v32
	v_rcp_f32_e32 v32, v8
	v_fmac_f32_e32 v40, v37, v37
	v_fmac_f32_e32 v42, v41, v41
	v_add_f32_e32 v56, v40, v42
	v_lshlrev_b32_e32 v40, 16, v9
	v_mul_f32_e32 v8, 0xbfb8aa3b, v40
	v_and_b32_e32 v42, 0xffff0000, v9
	v_pk_mul_f32 v[32:33], v[32:33], v[38:39]
	v_exp_f32_e32 v8, v8
	v_mul_f32_e32 v9, 0xbfb8aa3b, v42
	v_mul_f32_e32 v32, v32, v33
	v_exp_f32_e32 v33, v9
	v_add_f32_e32 v8, 1.0, v8
	v_rcp_f32_e32 v8, v8
	v_add_f32_e32 v54, 1.0, v54
	v_add_f32_e32 v33, 1.0, v33
	v_mov_b32_e32 v9, v34
	v_rcp_f32_e32 v34, v33
	v_rcp_f32_e32 v54, v54
	v_pk_mul_f32 v[8:9], v[8:9], v[40:41]
	v_mul_f32_e32 v41, v47, v53
	v_mul_f32_e32 v33, v8, v9
	v_pk_mul_f32 v[8:9], v[34:35], v[42:43]
	v_pk_mul_f32 v[36:37], v[54:55], v[36:37]
	v_mul_f32_e32 v8, v8, v9
	v_mul_f32_e32 v36, v36, v37
	v_cvt_pk_bf16_f32 v32, v36, v32
	v_cvt_pk_bf16_f32 v33, v33, v8
	v_lshlrev_b32_e32 v8, 16, v10
	v_mul_f32_e32 v36, 0xbfb8aa3b, v8
	v_exp_f32_e32 v42, v36
	v_and_b32_e32 v36, 0xffff0000, v10
	ds_write_b64 v51, v[32:33] offset:32
	v_mul_f32_e32 v10, 0xbfb8aa3b, v36
	ds_read_b128 v[32:35], v52 offset:96
	v_exp_f32_e32 v10, v10
	v_add_f32_e32 v42, 1.0, v42
	v_rcp_f32_e32 v42, v42
	v_mul_f32_e32 v37, v45, v53
	v_add_f32_e32 v10, 1.0, v10
	s_waitcnt lgkmcnt(0)
	v_mov_b32_e32 v43, v32
	v_rcp_f32_e32 v32, v10
	v_mul_f32_e32 v9, v44, v53
	v_mul_f32_e32 v39, v46, v53
	v_mul_f32_e32 v38, v37, v37
	v_mul_f32_e32 v40, v41, v41
	v_fmac_f32_e32 v38, v9, v9
	v_fmac_f32_e32 v40, v39, v39
	v_pk_mul_f32 v[8:9], v[42:43], v[8:9]
	v_add_f32_e32 v44, v38, v40
	v_mul_f32_e32 v10, v8, v9
	v_pk_mul_f32 v[8:9], v[32:33], v[36:37]
	v_lshlrev_b32_e32 v38, 16, v11
	v_mul_f32_e32 v32, v8, v9
	v_mul_f32_e32 v8, 0xbfb8aa3b, v38
	v_and_b32_e32 v40, 0xffff0000, v11
	v_exp_f32_e32 v8, v8
	v_mul_f32_e32 v9, 0xbfb8aa3b, v40
	v_exp_f32_e32 v11, v9
	v_mov_b32_e32 v9, v34
	v_add_f32_e32 v8, 1.0, v8
	v_rcp_f32_e32 v8, v8
	v_add_f32_e32 v11, 1.0, v11
	v_rcp_f32_e32 v34, v11
	v_cvt_pk_bf16_f32 v10, v10, v32
	v_lshlrev_b32_e32 v32, 16, v4
	v_pk_mul_f32 v[8:9], v[8:9], v[38:39]
	v_mul_f32_e32 v33, v16, v53
	v_mul_f32_e32 v16, 0xbfb8aa3b, v32
	v_mul_f32_e32 v11, v8, v9
	v_pk_mul_f32 v[8:9], v[34:35], v[40:41]
	v_exp_f32_e32 v36, v16
	v_and_b32_e32 v16, 0xffff0000, v4
	v_mul_f32_e32 v8, v8, v9
	v_cvt_pk_bf16_f32 v11, v11, v8
	ds_write_b64 v51, v[10:11] offset:48
	v_mul_f32_e32 v4, 0xbfb8aa3b, v16
	ds_read_b128 v[8:11], v52 offset:128
	v_exp_f32_e32 v4, v4
	v_mul_f32_e32 v17, v17, v53
	v_mul_f32_e32 v19, v19, v53
	v_mul_f32_e32 v35, v18, v53
	v_add_f32_e32 v4, 1.0, v4
	v_mul_f32_e32 v18, v17, v17
	v_mul_f32_e32 v34, v19, v19
	s_waitcnt lgkmcnt(0)
	v_mov_b32_e32 v37, v8
	v_rcp_f32_e32 v8, v4
	v_fmac_f32_e32 v18, v33, v33
	v_fmac_f32_e32 v34, v35, v35
	v_add_f32_e32 v38, v18, v34
	v_lshlrev_b32_e32 v34, 16, v5
	v_mul_f32_e32 v4, 0xbfb8aa3b, v34
	v_and_b32_e32 v18, 0xffff0000, v5
	v_pk_mul_f32 v[8:9], v[8:9], v[16:17]
	v_exp_f32_e32 v4, v4
	v_mul_f32_e32 v5, 0xbfb8aa3b, v18
	v_mul_f32_e32 v8, v8, v9
	v_exp_f32_e32 v9, v5
	v_add_f32_e32 v4, 1.0, v4
	v_rcp_f32_e32 v4, v4
	v_add_f32_e32 v36, 1.0, v36
	v_add_f32_e32 v9, 1.0, v9
	v_mov_b32_e32 v5, v10
	v_rcp_f32_e32 v10, v9
	v_rcp_f32_e32 v36, v36
	v_pk_mul_f32 v[4:5], v[4:5], v[34:35]
	v_mul_f32_e32 v17, v21, v53
	v_mul_f32_e32 v9, v4, v5
	v_pk_mul_f32 v[4:5], v[10:11], v[18:19]
	v_pk_mul_f32 v[32:33], v[36:37], v[32:33]
	v_mul_f32_e32 v4, v4, v5
	v_mul_f32_e32 v32, v32, v33
	v_cvt_pk_bf16_f32 v8, v32, v8
	v_cvt_pk_bf16_f32 v9, v9, v4
	v_lshlrev_b32_e32 v4, 16, v6
	v_mul_f32_e32 v16, 0xbfb8aa3b, v4
	v_mul_f32_e32 v19, v22, v53
	v_exp_f32_e32 v22, v16
	v_and_b32_e32 v16, 0xffff0000, v6
	ds_write_b64 v51, v[8:9] offset:64
	v_mul_f32_e32 v6, 0xbfb8aa3b, v16
	ds_read_b128 v[8:11], v52 offset:160
	v_exp_f32_e32 v6, v6
	v_add_f32_e32 v22, 1.0, v22
	v_rcp_f32_e32 v22, v22
	v_mul_f32_e32 v21, v23, v53
	v_add_f32_e32 v6, 1.0, v6
	s_waitcnt lgkmcnt(0)
; #define LAS __attribute__((address_space(3)))
; __device__ __forceinline__ unsigned pk2(float lo, float hi) { return pg8::cvt_pk_bf16(lo, hi); }
; __device__ __forceinline__ float bflo(unsigned w) { return __uint_as_float(w << 16); }
; __device__ __forceinline__ float bfhi(unsigned w) { return __uint_as_float(w & 0xffff0000u); }
; __device__ __forceinline__ float silu(float g) { return g * __builtin_amdgcn_rcpf(1.0f + __builtin_amdgcn_exp2f(-1.4426950408889634f * g)); }
; __device__ __forceinline__ void attn_unit(LAS unsigned char* lds, int unit, int mode, const bf16* QKVG, const float* sinks, const float* gain_a, bf16* MIX, float* SSA) {
;     ...
;         for (int e = 0; e < 8; ++e) gt[e] = *(const LAS v2u*)(wt_frd + 32 * (e >> 2) + 8 * (e & 3));
; #pragma unroll
;         for (int e = 0; e < 8; ++e) {
;             const int db = e >> 2, g4 = e & 3;
;             const float o0 = ot[db][4 * g4 + 0] * inv, o1 = ot[db][4 * g4 + 1] * inv, o2 = ot[db][4 * g4 + 2] * inv, o3 = ot[db][4 * g4 + 3] * inv;
;             ss += (o0 * o0 + o1 * o1) + (o2 * o2 + o3 * o3);
;             const f32x4 gn = *(const LAS f32x4*)(GN + 4 * hh + 32 * db + 8 * g4);
;             v2u z; z.x = pk2(o0 * gn[0] * silu(bflo(gt[e].x)), o1 * gn[1] * silu(bfhi(gt[e].x)));
;             z.y = pk2(o2 * gn[2] * silu(bflo(gt[e].y)), o3 * gn[3] * silu(bfhi(gt[e].y)));
;             *(LAS v2u*)(wt_frd + 32 * db + 8 * g4) = z;
;         }
;         {
;             bf16* orow0 = MIX + (size_t)(T0 + 32 * i + r8) * DMIX + 1024 + h * 64 + 8 * c8;
; #pragma unroll
;             for (int k = 0; k < 4; ++k) { const v4u v = *(const LAS v4u*)(wt_row + 8 * k * KP); *(v4u*)(orow0 + (size_t)(8 * k) * DMIX) = v; }
;         }
; #pragma unroll
;         for (int k = 0; k < 4; ++k) *(LAS v4u*)(wt_row + 8 * k * KP) = qrow[k];
;         ss += __shfl_xor(ss, 32);
;         if (hh == 0) SS[w * 128 + 32 * i + q] = ss;
	v_mov_b32_e32 v23, v8
	v_rcp_f32_e32 v8, v6
	v_mul_f32_e32 v5, v20, v53
	v_mul_f32_e32 v18, v17, v17
	v_mul_f32_e32 v20, v21, v21
	v_fmac_f32_e32 v18, v5, v5
	v_fmac_f32_e32 v20, v19, v19
	v_pk_mul_f32 v[4:5], v[22:23], v[4:5]
	v_add_f32_e32 v32, v18, v20
	v_mul_f32_e32 v6, v4, v5
	v_pk_mul_f32 v[4:5], v[8:9], v[16:17]
	v_lshlrev_b32_e32 v18, 16, v7
	v_mul_f32_e32 v8, v4, v5
	v_mul_f32_e32 v4, 0xbfb8aa3b, v18
	v_and_b32_e32 v20, 0xffff0000, v7
	v_exp_f32_e32 v4, v4
	v_mul_f32_e32 v5, 0xbfb8aa3b, v20
	v_exp_f32_e32 v7, v5
	v_mov_b32_e32 v5, v10
	v_add_f32_e32 v4, 1.0, v4
	v_rcp_f32_e32 v4, v4
	v_add_f32_e32 v7, 1.0, v7
	v_rcp_f32_e32 v10, v7
	v_cvt_pk_bf16_f32 v6, v6, v8
	v_pk_mul_f32 v[4:5], v[4:5], v[18:19]
	v_lshlrev_b32_e32 v8, 16, v0
	v_mul_f32_e32 v7, v4, v5
	v_pk_mul_f32 v[4:5], v[10:11], v[20:21]
	v_mul_f32_e32 v10, 0xbfb8aa3b, v8
	v_exp_f32_e32 v20, v10
	v_and_b32_e32 v10, 0xffff0000, v0
	v_mul_f32_e32 v4, v4, v5
	v_cvt_pk_bf16_f32 v7, v7, v4
	ds_write_b64 v51, v[6:7] offset:80
	v_mul_f32_e32 v0, 0xbfb8aa3b, v10
	ds_read_b128 v[4:7], v52 offset:192
	v_exp_f32_e32 v0, v0
	v_mul_f32_e32 v11, v25, v53
	v_mul_f32_e32 v19, v27, v53
	v_mul_f32_e32 v9, v24, v53
	v_add_f32_e32 v0, 1.0, v0
	v_mul_f32_e32 v17, v26, v53
	v_mul_f32_e32 v16, v11, v11
	v_mul_f32_e32 v18, v19, v19
	s_waitcnt lgkmcnt(0)
	v_mov_b32_e32 v21, v4
	v_rcp_f32_e32 v4, v0
	v_fmac_f32_e32 v16, v9, v9
	v_fmac_f32_e32 v18, v17, v17
	v_add_f32_e32 v22, v16, v18
	v_lshlrev_b32_e32 v16, 16, v1
	v_mul_f32_e32 v0, 0xbfb8aa3b, v16
	v_and_b32_e32 v18, 0xffff0000, v1
	v_pk_mul_f32 v[4:5], v[4:5], v[10:11]
	v_exp_f32_e32 v0, v0
	v_mul_f32_e32 v1, 0xbfb8aa3b, v18
	v_mul_f32_e32 v4, v4, v5
	v_exp_f32_e32 v5, v1
	v_add_f32_e32 v0, 1.0, v0
	v_rcp_f32_e32 v0, v0
	v_add_f32_e32 v20, 1.0, v20
	v_add_f32_e32 v5, 1.0, v5
	v_mov_b32_e32 v1, v6
	v_rcp_f32_e32 v6, v5
	v_rcp_f32_e32 v20, v20
	v_pk_mul_f32 v[0:1], v[0:1], v[16:17]
	v_mul_f32_e32 v17, v31, v53
	v_mul_f32_e32 v5, v0, v1
	v_pk_mul_f32 v[0:1], v[6:7], v[18:19]
	v_pk_mul_f32 v[8:9], v[20:21], v[8:9]
	v_mul_f32_e32 v0, v0, v1
	v_mul_f32_e32 v8, v8, v9
	v_cvt_pk_bf16_f32 v4, v8, v4
	v_cvt_pk_bf16_f32 v5, v5, v0
	v_lshlrev_b32_e32 v0, 16, v2
	v_mul_f32_e32 v8, 0xbfb8aa3b, v0
	v_exp_f32_e32 v18, v8
	v_and_b32_e32 v8, 0xffff0000, v2
	ds_write_b64 v51, v[4:5] offset:96
	v_mul_f32_e32 v2, 0xbfb8aa3b, v8
	ds_read_b128 v[4:7], v52 offset:224
	v_exp_f32_e32 v2, v2
	v_add_f32_e32 v18, 1.0, v18
	v_rcp_f32_e32 v18, v18
	v_mul_f32_e32 v9, v29, v53
	v_add_f32_e32 v2, 1.0, v2
	s_waitcnt lgkmcnt(0)
	v_mov_b32_e32 v19, v4
	v_rcp_f32_e32 v4, v2
	v_mul_f32_e32 v1, v28, v53
	v_mul_f32_e32 v11, v30, v53
	v_mul_f32_e32 v10, v9, v9
	v_mul_f32_e32 v16, v17, v17
	v_fmac_f32_e32 v10, v1, v1
	v_fmac_f32_e32 v16, v11, v11
	v_pk_mul_f32 v[0:1], v[18:19], v[0:1]
	v_add_f32_e32 v20, v10, v16
	v_mul_f32_e32 v2, v0, v1
	v_pk_mul_f32 v[0:1], v[4:5], v[8:9]
	v_lshlrev_b32_e32 v10, 16, v3
	v_mul_f32_e32 v4, v0, v1
	v_mul_f32_e32 v0, 0xbfb8aa3b, v10
	v_and_b32_e32 v16, 0xffff0000, v3
	v_exp_f32_e32 v0, v0
	v_mul_f32_e32 v1, 0xbfb8aa3b, v16
	v_exp_f32_e32 v3, v1
	v_mov_b32_e32 v1, v6
	v_add_f32_e32 v0, 1.0, v0
	v_rcp_f32_e32 v0, v0
	v_add_f32_e32 v3, 1.0, v3
	v_rcp_f32_e32 v6, v3
	v_cvt_pk_bf16_f32 v2, v2, v4
	v_pk_mul_f32 v[0:1], v[0:1], v[10:11]
	v_fmac_f32_e32 v14, v13, v13
	v_mul_f32_e32 v3, v0, v1
	v_pk_mul_f32 v[0:1], v[6:7], v[16:17]
	s_nop 0
	v_mul_f32_e32 v0, v0, v1
	v_cvt_pk_bf16_f32 v3, v3, v0
	ds_write_b64 v51, v[2:3] offset:112
	v_lshlrev_b64 v[0:1], 12, v[132:133]
	v_lshl_add_u64 v[4:5], s[94:95], 0, v[0:1]
	ds_read_b128 v[0:3], v137
	v_lshl_add_u64 v[4:5], v[4:5], 0, s[0:1]
	v_lshl_add_u64 v[8:9], v[130:131], 1, v[4:5]
	ds_read_b128 v[4:7], v137 offset:1152
	s_mov_b32 s0, 0x8000
	s_waitcnt lgkmcnt(1)
	global_store_dwordx4 v[8:9], v[0:3], off offset:2048
	s_nop 1
	v_add_co_u32_e64 v0, s[4:5], s0, v8
	s_mov_b32 s0, 0x10000
	s_nop 0
	v_addc_co_u32_e64 v1, s[4:5], 0, v9, s[4:5]
	s_waitcnt lgkmcnt(0)
	global_store_dwordx4 v[0:1], v[4:7], off offset:2048
	ds_read_b128 v[0:3], v137 offset:2304
	ds_read_b128 v[4:7], v137 offset:3456
	v_add_co_u32_e64 v10, s[4:5], s0, v8
	s_mov_b32 s0, 0x18000
	s_nop 0
	v_addc_co_u32_e64 v11, s[4:5], 0, v9, s[4:5]
	s_waitcnt lgkmcnt(1)
	global_store_dwordx4 v[10:11], v[0:3], off offset:2048
	s_nop 1
	v_add_co_u32_e64 v0, s[4:5], s0, v8
	s_nop 1
	v_addc_co_u32_e64 v1, s[4:5], 0, v9, s[4:5]
	s_waitcnt lgkmcnt(0)
	global_store_dwordx4 v[0:1], v[4:7], off offset:2048
	v_add_f32_e32 v0, v14, v15
	v_add_f32_e32 v0, v0, v12
	v_add_f32_e32 v0, v56, v0
	v_add_f32_e32 v0, v44, v0
	v_add_f32_e32 v0, v38, v0
	v_add_f32_e32 v0, v32, v0
	v_add_f32_e32 v0, v22, v0
	v_add_f32_e32 v0, v20, v0
	ds_bpermute_b32 v1, v48, v0
	ds_write_b128 v137, v[82:85]
	ds_write_b128 v137, v[86:89] offset:1152
	ds_write_b128 v137, v[90:93] offset:2304
	ds_write_b128 v137, v[94:97] offset:3456
	s_and_saveexec_b64 s[0:1], vcc
	s_cbranch_execz .LBB0_311
	s_lshl_b32 s3, s13, 9
	s_add_i32 s3, s3, 0
	s_lshl_b32 s4, s15, 2
	s_add_i32 s3, s3, s4
	s_waitcnt lgkmcnt(4)
	v_add_f32_e32 v0, v0, v1
	v_lshl_add_u32 v1, v134, 2, s3
	v_add_u32_e32 v1, 0x11400, v1
	ds_write_b32 v1, v0
